# convert_layer loads batched; write-through weight copies and no L2 write-back at the layer barrier
# speedup vs baseline: 1.0029x; 1.0029x over previous
; #define LAS __attribute__((address_space(3)))
; #define LDS_WAIT() asm volatile("s_waitcnt lgkmcnt(0)" ::: "memory")
; template <class T> __device__ __forceinline__ T ntload(const T* p) { return __builtin_nontemporal_load(p); }
; __device__ __forceinline__ void tr_item(const float* W, int ldw, int k0, int n0, bf16_t* WT, int ldt, int drow0, LAS float* scr, int lane) {
; #pragma unroll 8
;     for (int i = 0; i < 32; ++i) { const int kk = 2 * i + (lane >> 5); scr[kk * 33 + (lane & 31)] = ntload(W + (size_t)(k0 + kk) * ldw + n0 + (lane & 31)); }
;     LDS_WAIT();
; __device__ __forceinline__ void convert_layer(int l, LAS unsigned char* lds, int sw) {
;     ...
;             else { const int r = it - 3072, kb = r >> 5, nb = r & 31;
;                 tr_item(argp(I_AWOUT) + (size_t)j * 2048 * 1024, 1024, 64 * kb, 32 * nb, Wout, 2048, 32 * nb, scr, lane); }
.LBB0_33:
	v_lshl_add_u64 v[48:49], v[22:23], 0, s[4:5]
	v_lshl_add_u64 v[50:51], v[20:21], 0, s[4:5]
	v_lshl_add_u64 v[52:53], v[18:19], 0, s[4:5]
	v_lshl_add_u64 v[54:55], v[16:17], 0, s[4:5]
	v_lshl_add_u64 v[56:57], v[14:15], 0, s[4:5]
	v_lshl_add_u64 v[58:59], v[12:13], 0, s[4:5]
	v_lshl_add_u64 v[60:61], v[10:11], 0, s[4:5]
	v_lshl_add_u64 v[62:63], v[8:9], 0, s[4:5]
	global_load_dword v100, v[48:49], off nt
	global_load_dword v101, v[50:51], off nt
	global_load_dword v102, v[52:53], off nt
	global_load_dword v103, v[54:55], off nt
	global_load_dword v104, v[56:57], off nt
	global_load_dword v105, v[58:59], off nt
	global_load_dword v106, v[60:61], off nt
	global_load_dword v107, v[62:63], off nt
	s_add_u32 s4, s4, 0x10000
	s_addc_u32 s5, s5, 0
	v_lshl_add_u64 v[48:49], v[22:23], 0, s[4:5]
	v_lshl_add_u64 v[50:51], v[20:21], 0, s[4:5]
	v_lshl_add_u64 v[52:53], v[18:19], 0, s[4:5]
	v_lshl_add_u64 v[54:55], v[16:17], 0, s[4:5]
	v_lshl_add_u64 v[56:57], v[14:15], 0, s[4:5]
	v_lshl_add_u64 v[58:59], v[12:13], 0, s[4:5]
	v_lshl_add_u64 v[60:61], v[10:11], 0, s[4:5]
	v_lshl_add_u64 v[62:63], v[8:9], 0, s[4:5]
	global_load_dword v108, v[48:49], off nt
	global_load_dword v109, v[50:51], off nt
	global_load_dword v110, v[52:53], off nt
	global_load_dword v111, v[54:55], off nt
	global_load_dword v112, v[56:57], off nt
	global_load_dword v113, v[58:59], off nt
	global_load_dword v114, v[60:61], off nt
	global_load_dword v115, v[62:63], off nt
	s_add_u32 s4, s4, 0x10000
	s_addc_u32 s5, s5, 0
	v_lshl_add_u64 v[48:49], v[22:23], 0, s[4:5]
	v_lshl_add_u64 v[50:51], v[20:21], 0, s[4:5]
	v_lshl_add_u64 v[52:53], v[18:19], 0, s[4:5]
	v_lshl_add_u64 v[54:55], v[16:17], 0, s[4:5]
	v_lshl_add_u64 v[56:57], v[14:15], 0, s[4:5]
	v_lshl_add_u64 v[58:59], v[12:13], 0, s[4:5]
	v_lshl_add_u64 v[60:61], v[10:11], 0, s[4:5]
	v_lshl_add_u64 v[62:63], v[8:9], 0, s[4:5]
	global_load_dword v116, v[48:49], off nt
	global_load_dword v117, v[50:51], off nt
	global_load_dword v118, v[52:53], off nt
	global_load_dword v119, v[54:55], off nt
	global_load_dword v120, v[56:57], off nt
	global_load_dword v121, v[58:59], off nt
	global_load_dword v122, v[60:61], off nt
	global_load_dword v123, v[62:63], off nt
	s_add_u32 s4, s4, 0x10000
	s_addc_u32 s5, s5, 0
	v_lshl_add_u64 v[48:49], v[22:23], 0, s[4:5]
	v_lshl_add_u64 v[50:51], v[20:21], 0, s[4:5]
	v_lshl_add_u64 v[52:53], v[18:19], 0, s[4:5]
	v_lshl_add_u64 v[54:55], v[16:17], 0, s[4:5]
	v_lshl_add_u64 v[56:57], v[14:15], 0, s[4:5]
	v_lshl_add_u64 v[58:59], v[12:13], 0, s[4:5]
	v_lshl_add_u64 v[60:61], v[10:11], 0, s[4:5]
	v_lshl_add_u64 v[62:63], v[8:9], 0, s[4:5]
	global_load_dword v124, v[48:49], off nt
	global_load_dword v125, v[50:51], off nt
	global_load_dword v126, v[52:53], off nt
	global_load_dword v127, v[54:55], off nt
	global_load_dword v128, v[56:57], off nt
	global_load_dword v129, v[58:59], off nt
	global_load_dword v130, v[60:61], off nt
	global_load_dword v131, v[62:63], off nt
	s_add_u32 s4, s4, 0x10000
	s_addc_u32 s5, s5, 0
	v_add_u32_e32 v48, 0x400, v46
	s_waitcnt vmcnt(30)
	ds_write2_b32 v46, v100, v101 offset1:66
	s_waitcnt vmcnt(28)
	ds_write2_b32 v46, v102, v103 offset0:132 offset1:198
	s_waitcnt vmcnt(26)
	ds_write2_b32 v48, v104, v105 offset0:8 offset1:74
	s_waitcnt vmcnt(24)
	ds_write2_b32 v48, v106, v107 offset0:140 offset1:206
	v_add_u32_e32 v46, 0x840, v46
	v_add_u32_e32 v48, 0x400, v46
	s_waitcnt vmcnt(22)
	ds_write2_b32 v46, v108, v109 offset1:66
	s_waitcnt vmcnt(20)
	ds_write2_b32 v46, v110, v111 offset0:132 offset1:198
	s_waitcnt vmcnt(18)
; #define LAS __attribute__((address_space(3)))
; __device__ __forceinline__ unsigned cvt_pk_bf16(float lo, float hi) { unsigned r; asm volatile("v_cvt_pk_bf16_f32 %0, %1, %2" : "=v"(r) : "v"(lo), "v"(hi)); return r; }
; #define LDS_WAIT() asm volatile("s_waitcnt lgkmcnt(0)" ::: "memory")
; template <class T> __device__ __forceinline__ T ntload(const T* p) { return __builtin_nontemporal_load(p); }
; __device__ __forceinline__ void tr_item(const float* W, int ldw, int k0, int n0, bf16_t* WT, int ldt, int drow0, LAS float* scr, int lane) {
;     ...
;     for (int i = 0; i < 32; ++i) { const int kk = 2 * i + (lane >> 5); scr[kk * 33 + (lane & 31)] = ntload(W + (size_t)(k0 + kk) * ldw + n0 + (lane & 31)); }
;     LDS_WAIT();
;     const int c = lane & 7;
; #pragma unroll
;     for (int j = 0; j < 4; ++j) { const int n = (lane >> 3) + 8 * j; const LAS float* s = scr + (8 * c) * 33 + n;
;         u32x4 o; o.x = cvt_pk_bf16(s[0 * 33], s[1 * 33]); o.y = cvt_pk_bf16(s[2 * 33], s[3 * 33]); o.z = cvt_pk_bf16(s[4 * 33], s[5 * 33]); o.w = cvt_pk_bf16(s[6 * 33], s[7 * 33]);
;         *(u32x4*)(WT + (size_t)(drow0 + n) * ldt + k0 + 8 * c) = o; }
;     LDS_WAIT();
	ds_write2_b32 v48, v112, v113 offset0:8 offset1:74
	s_waitcnt vmcnt(16)
	ds_write2_b32 v48, v114, v115 offset0:140 offset1:206
	v_add_u32_e32 v46, 0x840, v46
	v_add_u32_e32 v48, 0x400, v46
	s_waitcnt vmcnt(14)
	ds_write2_b32 v46, v116, v117 offset1:66
	s_waitcnt vmcnt(12)
	ds_write2_b32 v46, v118, v119 offset0:132 offset1:198
	s_waitcnt vmcnt(10)
	ds_write2_b32 v48, v120, v121 offset0:8 offset1:74
	s_waitcnt vmcnt(8)
	ds_write2_b32 v48, v122, v123 offset0:140 offset1:206
	v_add_u32_e32 v46, 0x840, v46
	v_add_u32_e32 v48, 0x400, v46
	s_waitcnt vmcnt(6)
	ds_write2_b32 v46, v124, v125 offset1:66
	s_waitcnt vmcnt(4)
	ds_write2_b32 v46, v126, v127 offset0:132 offset1:198
	s_waitcnt vmcnt(2)
	ds_write2_b32 v48, v128, v129 offset0:8 offset1:74
	s_waitcnt vmcnt(0)
	ds_write2_b32 v48, v130, v131 offset0:140 offset1:206
	v_add_u32_e32 v46, 0x840, v46
	s_cmp_lg_u32 s4, 0x40000
	s_waitcnt lgkmcnt(0)
	ds_read2_b32 v[8:9], v26 offset1:33
	s_lshl_b32 s0, s10, 1
	s_lshl_b32 s4, s10, 5
	s_waitcnt lgkmcnt(0)
	v_cvt_pk_bf16_f32 v8, v8, v9
	ds_read2_b32 v[10:11], v26 offset0:66 offset1:99
	s_and_b32 s0, s0, 0x7fffffc0
	s_and_b32 s4, s4, 0x3e0
	s_waitcnt lgkmcnt(0)
	v_cvt_pk_bf16_f32 v9, v10, v11
	ds_read2_b32 v[10:11], v26 offset0:132 offset1:165
	s_addk_i32 s0, 0xe800
	v_or_b32_e32 v12, s4, v25
	v_mov_b32_e32 v13, v3
	s_waitcnt lgkmcnt(0)
	v_cvt_pk_bf16_f32 v10, v10, v11
	ds_read2_b32 v[14:15], v26 offset0:198 offset1:231
	v_lshl_add_u64 v[16:17], s[0:1], 1, v[4:5]
	v_lshlrev_b32_e32 v12, 12, v12
	s_waitcnt lgkmcnt(0)
	v_cvt_pk_bf16_f32 v11, v14, v15
	ds_read2_b32 v[14:15], v26 offset0:8 offset1:41
	v_lshl_add_u64 v[12:13], v[16:17], 0, v[12:13]
	global_store_dwordx4 v[12:13], v[8:11], off
	s_waitcnt lgkmcnt(0)
	s_nop 0
	v_cvt_pk_bf16_f32 v8, v14, v15
	ds_read2_b32 v[10:11], v26 offset0:74 offset1:107
	v_or_b32_e32 v14, s4, v27
	s_waitcnt lgkmcnt(0)
	v_cvt_pk_bf16_f32 v9, v10, v11
	ds_read2_b32 v[10:11], v26 offset0:140 offset1:173
	v_mov_b32_e32 v15, v3
	v_lshlrev_b32_e32 v14, 12, v14
	s_waitcnt lgkmcnt(0)
	v_cvt_pk_bf16_f32 v10, v10, v11
	ds_read2_b32 v[12:13], v26 offset0:206 offset1:239
	s_waitcnt lgkmcnt(0)
	v_cvt_pk_bf16_f32 v11, v12, v13
	v_lshl_add_u64 v[14:15], v[16:17], 0, v[14:15]
	ds_read2_b32 v[12:13], v26 offset0:16 offset1:49
	global_store_dwordx4 v[14:15], v[8:11], off
	v_or_b32_e32 v14, s4, v28
	v_mov_b32_e32 v15, v3
	s_waitcnt lgkmcnt(0)
	v_cvt_pk_bf16_f32 v8, v12, v13
	ds_read2_b32 v[10:11], v26 offset0:82 offset1:115
	s_waitcnt lgkmcnt(0)
	v_cvt_pk_bf16_f32 v9, v10, v11
	ds_read2_b32 v[10:11], v26 offset0:148 offset1:181
	v_lshlrev_b32_e32 v14, 12, v14
	s_waitcnt lgkmcnt(0)
	v_cvt_pk_bf16_f32 v10, v10, v11
	ds_read2_b32 v[12:13], v26 offset0:214 offset1:247
	s_waitcnt lgkmcnt(0)
	v_cvt_pk_bf16_f32 v11, v12, v13
	v_lshl_add_u64 v[14:15], v[16:17], 0, v[14:15]
	ds_read2_b32 v[12:13], v26 offset0:24 offset1:57
	global_store_dwordx4 v[14:15], v[8:11], off
	v_mov_b32_e32 v15, v3
	s_waitcnt lgkmcnt(0)
	v_cvt_pk_bf16_f32 v8, v12, v13
	ds_read2_b32 v[10:11], v26 offset0:90 offset1:123
	s_waitcnt lgkmcnt(0)
	v_cvt_pk_bf16_f32 v9, v10, v11
	ds_read2_b32 v[10:11], v26 offset0:156 offset1:189
	s_waitcnt lgkmcnt(0)
	v_cvt_pk_bf16_f32 v10, v10, v11
	v_or_b32_e32 v11, s4, v29
	ds_read2_b32 v[12:13], v26 offset0:222 offset1:255
	v_lshlrev_b32_e32 v14, 12, v11
	s_waitcnt lgkmcnt(0)
	v_cvt_pk_bf16_f32 v11, v12, v13
	v_lshl_add_u64 v[12:13], v[16:17], 0, v[14:15]
	global_store_dwordx4 v[12:13], v[8:11], off
	s_waitcnt lgkmcnt(0)
	s_mov_b64 s[4:5], 0

; #define LAS __attribute__((address_space(3)))
; #define LDS_WAIT() asm volatile("s_waitcnt lgkmcnt(0)" ::: "memory")
; template <class T> __device__ __forceinline__ T ntload(const T* p) { return __builtin_nontemporal_load(p); }
; __device__ __forceinline__ void tr_item(const float* W, int ldw, int k0, int n0, bf16_t* WT, int ldt, int drow0, LAS float* scr, int lane) {
; #pragma unroll 8
;     for (int i = 0; i < 32; ++i) { const int kk = 2 * i + (lane >> 5); scr[kk * 33 + (lane & 31)] = ntload(W + (size_t)(k0 + kk) * ldw + n0 + (lane & 31)); }
;     LDS_WAIT();
; __device__ __forceinline__ void convert_layer(int l, LAS unsigned char* lds, int sw) {
;     ...
;             if (it < 3072) { const int kb = it / 192, nb = it % 192, n0 = 32 * nb; bf16_t* dst; int drow0;
;                 if (n0 < 2048) { dst = Wug; drow0 = 256 * (n0 >> 7) + (n0 & 127); }
;                 else if (n0 < 4096) { dst = Wv; drow0 = n0 - 2048; }
;                 else { const int c = n0 - 4096; dst = Wug; drow0 = 256 * (c >> 7) + 128 + (c & 127); }
;                 tr_item(argp(I_AWIN) + (size_t)j * 1024 * 6144, 6144, 64 * kb, n0, dst, 1024, drow0, scr, lane); }
.LBB0_45:
	v_lshl_add_u64 v[48:49], v[22:23], 0, s[8:9]
	v_lshl_add_u64 v[50:51], v[20:21], 0, s[8:9]
	v_lshl_add_u64 v[52:53], v[18:19], 0, s[8:9]
	v_lshl_add_u64 v[54:55], v[16:17], 0, s[8:9]
	v_lshl_add_u64 v[56:57], v[14:15], 0, s[8:9]
	v_lshl_add_u64 v[58:59], v[12:13], 0, s[8:9]
	v_lshl_add_u64 v[60:61], v[10:11], 0, s[8:9]
	v_lshl_add_u64 v[62:63], v[8:9], 0, s[8:9]
	global_load_dword v100, v[48:49], off nt
	global_load_dword v101, v[50:51], off nt
	global_load_dword v102, v[52:53], off nt
	global_load_dword v103, v[54:55], off nt
	global_load_dword v104, v[56:57], off nt
	global_load_dword v105, v[58:59], off nt
	global_load_dword v106, v[60:61], off nt
	global_load_dword v107, v[62:63], off nt
	s_add_u32 s8, s8, 0x60000
	s_addc_u32 s9, s9, 0
	v_lshl_add_u64 v[48:49], v[22:23], 0, s[8:9]
	v_lshl_add_u64 v[50:51], v[20:21], 0, s[8:9]
	v_lshl_add_u64 v[52:53], v[18:19], 0, s[8:9]
	v_lshl_add_u64 v[54:55], v[16:17], 0, s[8:9]
	v_lshl_add_u64 v[56:57], v[14:15], 0, s[8:9]
	v_lshl_add_u64 v[58:59], v[12:13], 0, s[8:9]
	v_lshl_add_u64 v[60:61], v[10:11], 0, s[8:9]
	v_lshl_add_u64 v[62:63], v[8:9], 0, s[8:9]
	global_load_dword v108, v[48:49], off nt
	global_load_dword v109, v[50:51], off nt
	global_load_dword v110, v[52:53], off nt
	global_load_dword v111, v[54:55], off nt
	global_load_dword v112, v[56:57], off nt
	global_load_dword v113, v[58:59], off nt
	global_load_dword v114, v[60:61], off nt
	global_load_dword v115, v[62:63], off nt
	s_add_u32 s8, s8, 0x60000
	s_addc_u32 s9, s9, 0
	v_lshl_add_u64 v[48:49], v[22:23], 0, s[8:9]
	v_lshl_add_u64 v[50:51], v[20:21], 0, s[8:9]
	v_lshl_add_u64 v[52:53], v[18:19], 0, s[8:9]
	v_lshl_add_u64 v[54:55], v[16:17], 0, s[8:9]
	v_lshl_add_u64 v[56:57], v[14:15], 0, s[8:9]
	v_lshl_add_u64 v[58:59], v[12:13], 0, s[8:9]
	v_lshl_add_u64 v[60:61], v[10:11], 0, s[8:9]
	v_lshl_add_u64 v[62:63], v[8:9], 0, s[8:9]
	global_load_dword v116, v[48:49], off nt
	global_load_dword v117, v[50:51], off nt
	global_load_dword v118, v[52:53], off nt
	global_load_dword v119, v[54:55], off nt
	global_load_dword v120, v[56:57], off nt
	global_load_dword v121, v[58:59], off nt
	global_load_dword v122, v[60:61], off nt
	global_load_dword v123, v[62:63], off nt
	s_add_u32 s8, s8, 0x60000
	s_addc_u32 s9, s9, 0
	v_lshl_add_u64 v[48:49], v[22:23], 0, s[8:9]
	v_lshl_add_u64 v[50:51], v[20:21], 0, s[8:9]
	v_lshl_add_u64 v[52:53], v[18:19], 0, s[8:9]
	v_lshl_add_u64 v[54:55], v[16:17], 0, s[8:9]
	v_lshl_add_u64 v[56:57], v[14:15], 0, s[8:9]
	v_lshl_add_u64 v[58:59], v[12:13], 0, s[8:9]
	v_lshl_add_u64 v[60:61], v[10:11], 0, s[8:9]
	v_lshl_add_u64 v[62:63], v[8:9], 0, s[8:9]
	global_load_dword v124, v[48:49], off nt
	global_load_dword v125, v[50:51], off nt
	global_load_dword v126, v[52:53], off nt
	global_load_dword v127, v[54:55], off nt
	global_load_dword v128, v[56:57], off nt
	global_load_dword v129, v[58:59], off nt
	global_load_dword v130, v[60:61], off nt
	global_load_dword v131, v[62:63], off nt
	s_add_u32 s8, s8, 0x60000
	s_addc_u32 s9, s9, 0
	v_add_u32_e32 v48, 0x400, v46
	s_waitcnt vmcnt(30)
	ds_write2_b32 v46, v100, v101 offset1:66
	s_waitcnt vmcnt(28)
	ds_write2_b32 v46, v102, v103 offset0:132 offset1:198
	s_waitcnt vmcnt(26)
	ds_write2_b32 v48, v104, v105 offset0:8 offset1:74
	s_waitcnt vmcnt(24)
	ds_write2_b32 v48, v106, v107 offset0:140 offset1:206
	v_add_u32_e32 v46, 0x840, v46
	v_add_u32_e32 v48, 0x400, v46
	s_waitcnt vmcnt(22)
	ds_write2_b32 v46, v108, v109 offset1:66
	s_waitcnt vmcnt(20)
	ds_write2_b32 v46, v110, v111 offset0:132 offset1:198
	s_waitcnt vmcnt(18)
; #define LAS __attribute__((address_space(3)))
; __device__ __forceinline__ unsigned cvt_pk_bf16(float lo, float hi) { unsigned r; asm volatile("v_cvt_pk_bf16_f32 %0, %1, %2" : "=v"(r) : "v"(lo), "v"(hi)); return r; }
; #define LDS_WAIT() asm volatile("s_waitcnt lgkmcnt(0)" ::: "memory")
; __device__ __forceinline__ void tr_item(const float* W, int ldw, int k0, int n0, bf16_t* WT, int ldt, int drow0, LAS float* scr, int lane) {
;     ...
;     const int c = lane & 7;
; #pragma unroll
;     for (int j = 0; j < 4; ++j) { const int n = (lane >> 3) + 8 * j; const LAS float* s = scr + (8 * c) * 33 + n;
;         u32x4 o; o.x = cvt_pk_bf16(s[0 * 33], s[1 * 33]); o.y = cvt_pk_bf16(s[2 * 33], s[3 * 33]); o.z = cvt_pk_bf16(s[4 * 33], s[5 * 33]); o.w = cvt_pk_bf16(s[6 * 33], s[7 * 33]);
;         *(u32x4*)(WT + (size_t)(drow0 + n) * ldt + k0 + 8 * c) = o; }
;     LDS_WAIT();
; __device__ __forceinline__ void convert_layer(int l, LAS unsigned char* lds, int sw) {
;     ...
;         for (int it = gw; it < 4096; it += NGW) {
;             if (it < 3072) { const int kb = it / 192, nb = it % 192, n0 = 32 * nb; bf16_t* dst; int drow0;
;                 if (n0 < 2048) { dst = Wug; drow0 = 256 * (n0 >> 7) + (n0 & 127); }
;                 else if (n0 < 4096) { dst = Wv; drow0 = n0 - 2048; }
;                 else { const int c = n0 - 4096; dst = Wug; drow0 = 256 * (c >> 7) + 128 + (c & 127); }
;                 tr_item(argp(I_AWIN) + (size_t)j * 1024 * 6144, 6144, 64 * kb, n0, dst, 1024, drow0, scr, lane); }
	ds_write2_b32 v48, v112, v113 offset0:8 offset1:74
	s_waitcnt vmcnt(16)
	ds_write2_b32 v48, v114, v115 offset0:140 offset1:206
	v_add_u32_e32 v46, 0x840, v46
	v_add_u32_e32 v48, 0x400, v46
	s_waitcnt vmcnt(14)
	ds_write2_b32 v46, v116, v117 offset1:66
	s_waitcnt vmcnt(12)
	ds_write2_b32 v46, v118, v119 offset0:132 offset1:198
	s_waitcnt vmcnt(10)
	ds_write2_b32 v48, v120, v121 offset0:8 offset1:74
	s_waitcnt vmcnt(8)
	ds_write2_b32 v48, v122, v123 offset0:140 offset1:206
	v_add_u32_e32 v46, 0x840, v46
	v_add_u32_e32 v48, 0x400, v46
	s_waitcnt vmcnt(6)
	ds_write2_b32 v46, v124, v125 offset1:66
	s_waitcnt vmcnt(4)
	ds_write2_b32 v46, v126, v127 offset0:132 offset1:198
	s_waitcnt vmcnt(2)
	ds_write2_b32 v48, v128, v129 offset0:8 offset1:74
	s_waitcnt vmcnt(0)
	ds_write2_b32 v48, v130, v131 offset0:140 offset1:206
	v_add_u32_e32 v46, 0x840, v46
	s_cmp_lg_u32 s8, 0x180000
	s_add_u32 s8, s2, s4
	s_waitcnt lgkmcnt(0)
	s_addc_u32 s9, s3, s5
	s_ashr_i32 s7, s6, 31
	ds_read2_b32 v[8:9], v26 offset1:33
	s_lshl_b64 s[4:5], s[6:7], 1
	s_waitcnt lgkmcnt(0)
	v_cvt_pk_bf16_f32 v8, v8, v9
	ds_read2_b32 v[10:11], v26 offset0:66 offset1:99
	v_add_u32_e32 v12, s0, v25
	s_add_u32 s4, s8, s4
	s_waitcnt lgkmcnt(0)
	v_cvt_pk_bf16_f32 v9, v10, v11
	ds_read2_b32 v[10:11], v26 offset0:132 offset1:165
	v_ashrrev_i32_e32 v13, 31, v12
	s_addc_u32 s5, s9, s5
	s_waitcnt lgkmcnt(0)
	v_cvt_pk_bf16_f32 v10, v10, v11
	ds_read2_b32 v[14:15], v26 offset0:198 offset1:231
	v_lshlrev_b64 v[12:13], 11, v[12:13]
	v_lshl_add_u64 v[16:17], s[4:5], 0, v[2:3]
	s_waitcnt lgkmcnt(0)
	v_cvt_pk_bf16_f32 v11, v14, v15
	ds_read2_b32 v[14:15], v26 offset0:8 offset1:41
	v_lshl_add_u64 v[12:13], v[16:17], 0, v[12:13]
	global_store_dwordx4 v[12:13], v[8:11], off
	s_waitcnt lgkmcnt(0)
	s_nop 0
	v_cvt_pk_bf16_f32 v8, v14, v15
	v_add_u32_e32 v14, s0, v27
	v_ashrrev_i32_e32 v15, 31, v14
	ds_read2_b32 v[10:11], v26 offset0:74 offset1:107
	v_lshlrev_b64 v[14:15], 11, v[14:15]
	s_waitcnt lgkmcnt(0)
	v_cvt_pk_bf16_f32 v9, v10, v11
	ds_read2_b32 v[10:11], v26 offset0:140 offset1:173
	v_lshl_add_u64 v[14:15], v[16:17], 0, v[14:15]
	s_waitcnt lgkmcnt(0)
	v_cvt_pk_bf16_f32 v10, v10, v11
	ds_read2_b32 v[12:13], v26 offset0:206 offset1:239
	s_waitcnt lgkmcnt(0)
	v_cvt_pk_bf16_f32 v11, v12, v13
	global_store_dwordx4 v[14:15], v[8:11], off
	v_add_u32_e32 v14, s0, v28
	ds_read2_b32 v[12:13], v26 offset0:16 offset1:49
	s_waitcnt lgkmcnt(0)
	v_cvt_pk_bf16_f32 v8, v12, v13
	ds_read2_b32 v[10:11], v26 offset0:82 offset1:115
	v_ashrrev_i32_e32 v15, 31, v14
	s_waitcnt lgkmcnt(0)
	v_cvt_pk_bf16_f32 v9, v10, v11
	ds_read2_b32 v[10:11], v26 offset0:148 offset1:181
	v_lshlrev_b64 v[14:15], 11, v[14:15]
	s_waitcnt lgkmcnt(0)
	v_cvt_pk_bf16_f32 v10, v10, v11
	ds_read2_b32 v[12:13], v26 offset0:214 offset1:247
	s_waitcnt lgkmcnt(0)
	v_cvt_pk_bf16_f32 v11, v12, v13
	v_lshl_add_u64 v[14:15], v[16:17], 0, v[14:15]
	ds_read2_b32 v[12:13], v26 offset0:24 offset1:57
	global_store_dwordx4 v[14:15], v[8:11], off
	v_add_u32_e32 v14, s0, v29
	v_ashrrev_i32_e32 v15, 31, v14
	s_waitcnt lgkmcnt(0)
	v_cvt_pk_bf16_f32 v8, v12, v13
	ds_read2_b32 v[10:11], v26 offset0:90 offset1:123
	s_waitcnt lgkmcnt(0)
	v_cvt_pk_bf16_f32 v9, v10, v11
	ds_read2_b32 v[10:11], v26 offset0:156 offset1:189
	s_waitcnt lgkmcnt(0)
	v_cvt_pk_bf16_f32 v10, v10, v11
	ds_read2_b32 v[12:13], v26 offset0:222 offset1:255
	v_lshlrev_b64 v[14:15], 11, v[14:15]
	s_waitcnt lgkmcnt(0)
	v_cvt_pk_bf16_f32 v11, v12, v13
	v_lshl_add_u64 v[12:13], v[16:17], 0, v[14:15]
	global_store_dwordx4 v[12:13], v[8:11], off
	s_waitcnt lgkmcnt(0)
	s_branch .LBB0_30

; #define LAS __attribute__((address_space(3)))
; #define LDS_WAIT() asm volatile("s_waitcnt lgkmcnt(0)" ::: "memory")
; template <class T> __device__ __forceinline__ T ntload(const T* p) { return __builtin_nontemporal_load(p); }
; __device__ __forceinline__ void tr_item(const float* W, int ldw, int k0, int n0, bf16_t* WT, int ldt, int drow0, LAS float* scr, int lane) {
; #pragma unroll 8
;     for (int i = 0; i < 32; ++i) { const int kk = 2 * i + (lane >> 5); scr[kk * 33 + (lane & 31)] = ntload(W + (size_t)(k0 + kk) * ldw + n0 + (lane & 31)); }
;     LDS_WAIT();
; __device__ __forceinline__ void convert_layer(int l, LAS unsigned char* lds, int sw) {
;     ...
;             else { const int r = it - 3072, kb = r >> 5, nb = r & 31;
;                 tr_item(argp(I_AWOUT) + (size_t)j * 2048 * 1024, 1024, 64 * kb, 32 * nb, Wout, 2048, 32 * nb, scr, lane); }
.LBB0_1327:
	v_lshl_add_u64 v[50:51], v[22:23], 0, s[8:9]
	v_lshl_add_u64 v[52:53], v[20:21], 0, s[8:9]
	v_lshl_add_u64 v[54:55], v[18:19], 0, s[8:9]
	v_lshl_add_u64 v[56:57], v[16:17], 0, s[8:9]
	v_lshl_add_u64 v[58:59], v[14:15], 0, s[8:9]
	v_lshl_add_u64 v[60:61], v[12:13], 0, s[8:9]
	v_lshl_add_u64 v[62:63], v[10:11], 0, s[8:9]
	v_lshl_add_u64 v[64:65], v[8:9], 0, s[8:9]
	global_load_dword v100, v[50:51], off nt
	global_load_dword v101, v[52:53], off nt
	global_load_dword v102, v[54:55], off nt
	global_load_dword v103, v[56:57], off nt
	global_load_dword v104, v[58:59], off nt
	global_load_dword v105, v[60:61], off nt
	global_load_dword v106, v[62:63], off nt
	global_load_dword v107, v[64:65], off nt
	s_add_u32 s8, s8, 0x10000
	s_addc_u32 s9, s9, 0
	v_lshl_add_u64 v[50:51], v[22:23], 0, s[8:9]
	v_lshl_add_u64 v[52:53], v[20:21], 0, s[8:9]
	v_lshl_add_u64 v[54:55], v[18:19], 0, s[8:9]
	v_lshl_add_u64 v[56:57], v[16:17], 0, s[8:9]
	v_lshl_add_u64 v[58:59], v[14:15], 0, s[8:9]
	v_lshl_add_u64 v[60:61], v[12:13], 0, s[8:9]
	v_lshl_add_u64 v[62:63], v[10:11], 0, s[8:9]
	v_lshl_add_u64 v[64:65], v[8:9], 0, s[8:9]
	global_load_dword v108, v[50:51], off nt
	global_load_dword v109, v[52:53], off nt
	global_load_dword v110, v[54:55], off nt
	global_load_dword v111, v[56:57], off nt
	global_load_dword v112, v[58:59], off nt
	global_load_dword v113, v[60:61], off nt
	global_load_dword v114, v[62:63], off nt
	global_load_dword v115, v[64:65], off nt
	s_add_u32 s8, s8, 0x10000
	s_addc_u32 s9, s9, 0
	v_lshl_add_u64 v[50:51], v[22:23], 0, s[8:9]
	v_lshl_add_u64 v[52:53], v[20:21], 0, s[8:9]
	v_lshl_add_u64 v[54:55], v[18:19], 0, s[8:9]
	v_lshl_add_u64 v[56:57], v[16:17], 0, s[8:9]
	v_lshl_add_u64 v[58:59], v[14:15], 0, s[8:9]
	v_lshl_add_u64 v[60:61], v[12:13], 0, s[8:9]
	v_lshl_add_u64 v[62:63], v[10:11], 0, s[8:9]
	v_lshl_add_u64 v[64:65], v[8:9], 0, s[8:9]
	global_load_dword v116, v[50:51], off nt
	global_load_dword v117, v[52:53], off nt
	global_load_dword v118, v[54:55], off nt
	global_load_dword v119, v[56:57], off nt
	global_load_dword v120, v[58:59], off nt
	global_load_dword v121, v[60:61], off nt
	global_load_dword v122, v[62:63], off nt
	global_load_dword v123, v[64:65], off nt
	s_add_u32 s8, s8, 0x10000
	s_addc_u32 s9, s9, 0
	v_lshl_add_u64 v[50:51], v[22:23], 0, s[8:9]
	v_lshl_add_u64 v[52:53], v[20:21], 0, s[8:9]
	v_lshl_add_u64 v[54:55], v[18:19], 0, s[8:9]
	v_lshl_add_u64 v[56:57], v[16:17], 0, s[8:9]
	v_lshl_add_u64 v[58:59], v[14:15], 0, s[8:9]
	v_lshl_add_u64 v[60:61], v[12:13], 0, s[8:9]
	v_lshl_add_u64 v[62:63], v[10:11], 0, s[8:9]
	v_lshl_add_u64 v[64:65], v[8:9], 0, s[8:9]
	global_load_dword v124, v[50:51], off nt
	global_load_dword v125, v[52:53], off nt
	global_load_dword v126, v[54:55], off nt
	global_load_dword v127, v[56:57], off nt
	global_load_dword v128, v[58:59], off nt
	global_load_dword v129, v[60:61], off nt
	global_load_dword v130, v[62:63], off nt
	global_load_dword v131, v[64:65], off nt
	s_add_u32 s8, s8, 0x10000
	s_addc_u32 s9, s9, 0
	v_add_u32_e32 v57, 0x400, v48
	s_waitcnt vmcnt(30)
	ds_write2_b32 v48, v100, v101 offset1:66
	s_waitcnt vmcnt(28)
	ds_write2_b32 v48, v102, v103 offset0:132 offset1:198
	s_waitcnt vmcnt(26)
	ds_write2_b32 v57, v104, v105 offset0:8 offset1:74
	s_waitcnt vmcnt(24)
	ds_write2_b32 v57, v106, v107 offset0:140 offset1:206
	v_add_u32_e32 v48, 0x840, v48
	v_add_u32_e32 v57, 0x400, v48
	s_waitcnt vmcnt(22)
	ds_write2_b32 v48, v108, v109 offset1:66
	s_waitcnt vmcnt(20)
	ds_write2_b32 v48, v110, v111 offset0:132 offset1:198
	s_waitcnt vmcnt(18)
; #define LAS __attribute__((address_space(3)))
; __device__ __forceinline__ unsigned cvt_pk_bf16(float lo, float hi) { unsigned r; asm volatile("v_cvt_pk_bf16_f32 %0, %1, %2" : "=v"(r) : "v"(lo), "v"(hi)); return r; }
; #define LDS_WAIT() asm volatile("s_waitcnt lgkmcnt(0)" ::: "memory")
; template <class T> __device__ __forceinline__ T ntload(const T* p) { return __builtin_nontemporal_load(p); }
; __device__ __forceinline__ void tr_item(const float* W, int ldw, int k0, int n0, bf16_t* WT, int ldt, int drow0, LAS float* scr, int lane) {
;     ...
;     for (int i = 0; i < 32; ++i) { const int kk = 2 * i + (lane >> 5); scr[kk * 33 + (lane & 31)] = ntload(W + (size_t)(k0 + kk) * ldw + n0 + (lane & 31)); }
;     LDS_WAIT();
;     const int c = lane & 7;
; #pragma unroll
;     for (int j = 0; j < 4; ++j) { const int n = (lane >> 3) + 8 * j; const LAS float* s = scr + (8 * c) * 33 + n;
;         u32x4 o; o.x = cvt_pk_bf16(s[0 * 33], s[1 * 33]); o.y = cvt_pk_bf16(s[2 * 33], s[3 * 33]); o.z = cvt_pk_bf16(s[4 * 33], s[5 * 33]); o.w = cvt_pk_bf16(s[6 * 33], s[7 * 33]);
;         *(u32x4*)(WT + (size_t)(drow0 + n) * ldt + k0 + 8 * c) = o; }
;     LDS_WAIT();
	ds_write2_b32 v57, v112, v113 offset0:8 offset1:74
	s_waitcnt vmcnt(16)
	ds_write2_b32 v57, v114, v115 offset0:140 offset1:206
	v_add_u32_e32 v48, 0x840, v48
	v_add_u32_e32 v57, 0x400, v48
	s_waitcnt vmcnt(14)
	ds_write2_b32 v48, v116, v117 offset1:66
	s_waitcnt vmcnt(12)
	ds_write2_b32 v48, v118, v119 offset0:132 offset1:198
	s_waitcnt vmcnt(10)
	ds_write2_b32 v57, v120, v121 offset0:8 offset1:74
	s_waitcnt vmcnt(8)
	ds_write2_b32 v57, v122, v123 offset0:140 offset1:206
	v_add_u32_e32 v48, 0x840, v48
	v_add_u32_e32 v57, 0x400, v48
	s_waitcnt vmcnt(6)
	ds_write2_b32 v48, v124, v125 offset1:66
	s_waitcnt vmcnt(4)
	ds_write2_b32 v48, v126, v127 offset0:132 offset1:198
	s_waitcnt vmcnt(2)
	ds_write2_b32 v57, v128, v129 offset0:8 offset1:74
	s_waitcnt vmcnt(0)
	ds_write2_b32 v57, v130, v131 offset0:140 offset1:206
	v_add_u32_e32 v48, 0x840, v48
	s_cmp_lg_u32 s8, 0x40000
	s_waitcnt lgkmcnt(0)
	ds_read2_b32 v[8:9], v28 offset1:33
	s_lshl_b32 s8, s25, 1
	s_lshl_b32 s9, s25, 5
	s_waitcnt lgkmcnt(0)
	v_cvt_pk_bf16_f32 v8, v8, v9
	ds_read2_b32 v[10:11], v28 offset0:66 offset1:99
	s_and_b32 s10, s8, 0x7fffffc0
	s_and_b32 s8, s9, 0x3e0
	s_waitcnt lgkmcnt(0)
	v_cvt_pk_bf16_f32 v9, v10, v11
	ds_read2_b32 v[10:11], v28 offset0:132 offset1:165
	s_add_i32 s80, s10, 0xffffe800
	v_or_b32_e32 v12, s8, v27
	v_mov_b32_e32 v13, v1
	s_waitcnt lgkmcnt(0)
	v_cvt_pk_bf16_f32 v10, v10, v11
	ds_read2_b32 v[14:15], v28 offset0:198 offset1:231
	v_lshl_add_u64 v[16:17], s[80:81], 1, v[2:3]
	v_lshlrev_b32_e32 v12, 12, v12
	s_waitcnt lgkmcnt(0)
	v_cvt_pk_bf16_f32 v11, v14, v15
	ds_read2_b32 v[14:15], v28 offset0:8 offset1:41
	v_lshl_add_u64 v[12:13], v[16:17], 0, v[12:13]
	global_store_dwordx4 v[12:13], v[8:11], off sc0 sc1
	s_waitcnt lgkmcnt(0)
	s_nop 0
	v_cvt_pk_bf16_f32 v8, v14, v15
	ds_read2_b32 v[10:11], v28 offset0:74 offset1:107
	v_or_b32_e32 v14, s8, v29
	s_waitcnt lgkmcnt(0)
	v_cvt_pk_bf16_f32 v9, v10, v11
	ds_read2_b32 v[10:11], v28 offset0:140 offset1:173
	v_mov_b32_e32 v15, v1
	v_lshlrev_b32_e32 v14, 12, v14
	s_waitcnt lgkmcnt(0)
	v_cvt_pk_bf16_f32 v10, v10, v11
	ds_read2_b32 v[12:13], v28 offset0:206 offset1:239
	s_waitcnt lgkmcnt(0)
	v_cvt_pk_bf16_f32 v11, v12, v13
	v_lshl_add_u64 v[14:15], v[16:17], 0, v[14:15]
	ds_read2_b32 v[12:13], v28 offset0:16 offset1:49
	global_store_dwordx4 v[14:15], v[8:11], off sc0 sc1
	v_or_b32_e32 v14, s8, v30
	v_mov_b32_e32 v15, v1
	s_waitcnt lgkmcnt(0)
	v_cvt_pk_bf16_f32 v8, v12, v13
	ds_read2_b32 v[10:11], v28 offset0:82 offset1:115
	s_waitcnt lgkmcnt(0)
	v_cvt_pk_bf16_f32 v9, v10, v11
	ds_read2_b32 v[10:11], v28 offset0:148 offset1:181
	v_lshlrev_b32_e32 v14, 12, v14
	s_waitcnt lgkmcnt(0)
	v_cvt_pk_bf16_f32 v10, v10, v11
	ds_read2_b32 v[12:13], v28 offset0:214 offset1:247
	s_waitcnt lgkmcnt(0)
	v_cvt_pk_bf16_f32 v11, v12, v13
	v_lshl_add_u64 v[14:15], v[16:17], 0, v[14:15]
	ds_read2_b32 v[12:13], v28 offset0:24 offset1:57
	global_store_dwordx4 v[14:15], v[8:11], off sc0 sc1
	v_mov_b32_e32 v15, v1
	s_waitcnt lgkmcnt(0)
	v_cvt_pk_bf16_f32 v8, v12, v13
	ds_read2_b32 v[10:11], v28 offset0:90 offset1:123
	s_waitcnt lgkmcnt(0)
	v_cvt_pk_bf16_f32 v9, v10, v11
	ds_read2_b32 v[10:11], v28 offset0:156 offset1:189
	s_waitcnt lgkmcnt(0)
	v_cvt_pk_bf16_f32 v10, v10, v11
	v_or_b32_e32 v11, s8, v31
	ds_read2_b32 v[12:13], v28 offset0:222 offset1:255
	v_lshlrev_b32_e32 v14, 12, v11
	s_waitcnt lgkmcnt(0)
	v_cvt_pk_bf16_f32 v11, v12, v13
	v_lshl_add_u64 v[12:13], v[16:17], 0, v[14:15]
	global_store_dwordx4 v[12:13], v[8:11], off sc0 sc1
	s_waitcnt lgkmcnt(0)
	s_mov_b64 s[8:9], 0

; #define LAS __attribute__((address_space(3)))
; #define LDS_WAIT() asm volatile("s_waitcnt lgkmcnt(0)" ::: "memory")
; template <class T> __device__ __forceinline__ T ntload(const T* p) { return __builtin_nontemporal_load(p); }
; __device__ __forceinline__ void tr_item(const float* W, int ldw, int k0, int n0, bf16_t* WT, int ldt, int drow0, LAS float* scr, int lane) {
; #pragma unroll 8
;     for (int i = 0; i < 32; ++i) { const int kk = 2 * i + (lane >> 5); scr[kk * 33 + (lane & 31)] = ntload(W + (size_t)(k0 + kk) * ldw + n0 + (lane & 31)); }
;     LDS_WAIT();
; __device__ __forceinline__ void convert_layer(int l, LAS unsigned char* lds, int sw) {
;     ...
;             if (it < 3072) { const int kb = it / 192, nb = it % 192, n0 = 32 * nb; bf16_t* dst; int drow0;
;                 if (n0 < 2048) { dst = Wug; drow0 = 256 * (n0 >> 7) + (n0 & 127); }
;                 else if (n0 < 4096) { dst = Wv; drow0 = n0 - 2048; }
;                 else { const int c = n0 - 4096; dst = Wug; drow0 = 256 * (c >> 7) + 128 + (c & 127); }
;                 tr_item(argp(I_AWIN) + (size_t)j * 1024 * 6144, 6144, 64 * kb, n0, dst, 1024, drow0, scr, lane); }
.LBB0_1339:
	v_lshl_add_u64 v[50:51], v[22:23], 0, s[12:13]
	v_lshl_add_u64 v[52:53], v[20:21], 0, s[12:13]
	v_lshl_add_u64 v[54:55], v[18:19], 0, s[12:13]
	v_lshl_add_u64 v[56:57], v[16:17], 0, s[12:13]
	v_lshl_add_u64 v[58:59], v[14:15], 0, s[12:13]
	v_lshl_add_u64 v[60:61], v[12:13], 0, s[12:13]
	v_lshl_add_u64 v[62:63], v[10:11], 0, s[12:13]
	v_lshl_add_u64 v[64:65], v[8:9], 0, s[12:13]
	global_load_dword v100, v[50:51], off nt
	global_load_dword v101, v[52:53], off nt
	global_load_dword v102, v[54:55], off nt
	global_load_dword v103, v[56:57], off nt
	global_load_dword v104, v[58:59], off nt
	global_load_dword v105, v[60:61], off nt
	global_load_dword v106, v[62:63], off nt
	global_load_dword v107, v[64:65], off nt
	s_add_u32 s12, s12, 0x60000
	s_addc_u32 s13, s13, 0
	v_lshl_add_u64 v[50:51], v[22:23], 0, s[12:13]
	v_lshl_add_u64 v[52:53], v[20:21], 0, s[12:13]
	v_lshl_add_u64 v[54:55], v[18:19], 0, s[12:13]
	v_lshl_add_u64 v[56:57], v[16:17], 0, s[12:13]
	v_lshl_add_u64 v[58:59], v[14:15], 0, s[12:13]
	v_lshl_add_u64 v[60:61], v[12:13], 0, s[12:13]
	v_lshl_add_u64 v[62:63], v[10:11], 0, s[12:13]
	v_lshl_add_u64 v[64:65], v[8:9], 0, s[12:13]
	global_load_dword v108, v[50:51], off nt
	global_load_dword v109, v[52:53], off nt
	global_load_dword v110, v[54:55], off nt
	global_load_dword v111, v[56:57], off nt
	global_load_dword v112, v[58:59], off nt
	global_load_dword v113, v[60:61], off nt
	global_load_dword v114, v[62:63], off nt
	global_load_dword v115, v[64:65], off nt
	s_add_u32 s12, s12, 0x60000
	s_addc_u32 s13, s13, 0
	v_lshl_add_u64 v[50:51], v[22:23], 0, s[12:13]
	v_lshl_add_u64 v[52:53], v[20:21], 0, s[12:13]
	v_lshl_add_u64 v[54:55], v[18:19], 0, s[12:13]
	v_lshl_add_u64 v[56:57], v[16:17], 0, s[12:13]
	v_lshl_add_u64 v[58:59], v[14:15], 0, s[12:13]
	v_lshl_add_u64 v[60:61], v[12:13], 0, s[12:13]
	v_lshl_add_u64 v[62:63], v[10:11], 0, s[12:13]
	v_lshl_add_u64 v[64:65], v[8:9], 0, s[12:13]
	global_load_dword v116, v[50:51], off nt
	global_load_dword v117, v[52:53], off nt
	global_load_dword v118, v[54:55], off nt
	global_load_dword v119, v[56:57], off nt
	global_load_dword v120, v[58:59], off nt
	global_load_dword v121, v[60:61], off nt
	global_load_dword v122, v[62:63], off nt
	global_load_dword v123, v[64:65], off nt
	s_add_u32 s12, s12, 0x60000
	s_addc_u32 s13, s13, 0
	v_lshl_add_u64 v[50:51], v[22:23], 0, s[12:13]
	v_lshl_add_u64 v[52:53], v[20:21], 0, s[12:13]
	v_lshl_add_u64 v[54:55], v[18:19], 0, s[12:13]
	v_lshl_add_u64 v[56:57], v[16:17], 0, s[12:13]
	v_lshl_add_u64 v[58:59], v[14:15], 0, s[12:13]
	v_lshl_add_u64 v[60:61], v[12:13], 0, s[12:13]
	v_lshl_add_u64 v[62:63], v[10:11], 0, s[12:13]
	v_lshl_add_u64 v[64:65], v[8:9], 0, s[12:13]
	global_load_dword v124, v[50:51], off nt
	global_load_dword v125, v[52:53], off nt
	global_load_dword v126, v[54:55], off nt
	global_load_dword v127, v[56:57], off nt
	global_load_dword v128, v[58:59], off nt
	global_load_dword v129, v[60:61], off nt
	global_load_dword v130, v[62:63], off nt
	global_load_dword v131, v[64:65], off nt
	s_add_u32 s12, s12, 0x60000
	s_addc_u32 s13, s13, 0
	v_add_u32_e32 v57, 0x400, v48
	s_waitcnt vmcnt(30)
	ds_write2_b32 v48, v100, v101 offset1:66
	s_waitcnt vmcnt(28)
	ds_write2_b32 v48, v102, v103 offset0:132 offset1:198
	s_waitcnt vmcnt(26)
	ds_write2_b32 v57, v104, v105 offset0:8 offset1:74
	s_waitcnt vmcnt(24)
	ds_write2_b32 v57, v106, v107 offset0:140 offset1:206
	v_add_u32_e32 v48, 0x840, v48
	v_add_u32_e32 v57, 0x400, v48
	s_waitcnt vmcnt(22)
	ds_write2_b32 v48, v108, v109 offset1:66
	s_waitcnt vmcnt(20)
	ds_write2_b32 v48, v110, v111 offset0:132 offset1:198
	s_waitcnt vmcnt(18)
; #define LAS __attribute__((address_space(3)))
; __device__ __forceinline__ unsigned cvt_pk_bf16(float lo, float hi) { unsigned r; asm volatile("v_cvt_pk_bf16_f32 %0, %1, %2" : "=v"(r) : "v"(lo), "v"(hi)); return r; }
; #define LDS_WAIT() asm volatile("s_waitcnt lgkmcnt(0)" ::: "memory")
; __device__ __forceinline__ void tr_item(const float* W, int ldw, int k0, int n0, bf16_t* WT, int ldt, int drow0, LAS float* scr, int lane) {
;     ...
;     const int c = lane & 7;
; #pragma unroll
;     for (int j = 0; j < 4; ++j) { const int n = (lane >> 3) + 8 * j; const LAS float* s = scr + (8 * c) * 33 + n;
;         u32x4 o; o.x = cvt_pk_bf16(s[0 * 33], s[1 * 33]); o.y = cvt_pk_bf16(s[2 * 33], s[3 * 33]); o.z = cvt_pk_bf16(s[4 * 33], s[5 * 33]); o.w = cvt_pk_bf16(s[6 * 33], s[7 * 33]);
;         *(u32x4*)(WT + (size_t)(drow0 + n) * ldt + k0 + 8 * c) = o; }
;     LDS_WAIT();
; __device__ __forceinline__ void convert_layer(int l, LAS unsigned char* lds, int sw) {
;     ...
;         for (int it = gw; it < 4096; it += NGW) {
;             if (it < 3072) { const int kb = it / 192, nb = it % 192, n0 = 32 * nb; bf16_t* dst; int drow0;
;                 if (n0 < 2048) { dst = Wug; drow0 = 256 * (n0 >> 7) + (n0 & 127); }
;                 else if (n0 < 4096) { dst = Wv; drow0 = n0 - 2048; }
;                 else { const int c = n0 - 4096; dst = Wug; drow0 = 256 * (c >> 7) + 128 + (c & 127); }
;                 tr_item(argp(I_AWIN) + (size_t)j * 1024 * 6144, 6144, 64 * kb, n0, dst, 1024, drow0, scr, lane); }
	ds_write2_b32 v57, v112, v113 offset0:8 offset1:74
	s_waitcnt vmcnt(16)
	ds_write2_b32 v57, v114, v115 offset0:140 offset1:206
	v_add_u32_e32 v48, 0x840, v48
	v_add_u32_e32 v57, 0x400, v48
	s_waitcnt vmcnt(14)
	ds_write2_b32 v48, v116, v117 offset1:66
	s_waitcnt vmcnt(12)
	ds_write2_b32 v48, v118, v119 offset0:132 offset1:198
	s_waitcnt vmcnt(10)
	ds_write2_b32 v57, v120, v121 offset0:8 offset1:74
	s_waitcnt vmcnt(8)
	ds_write2_b32 v57, v122, v123 offset0:140 offset1:206
	v_add_u32_e32 v48, 0x840, v48
	v_add_u32_e32 v57, 0x400, v48
	s_waitcnt vmcnt(6)
	ds_write2_b32 v48, v124, v125 offset1:66
	s_waitcnt vmcnt(4)
	ds_write2_b32 v48, v126, v127 offset0:132 offset1:198
	s_waitcnt vmcnt(2)
	ds_write2_b32 v57, v128, v129 offset0:8 offset1:74
	s_waitcnt vmcnt(0)
	ds_write2_b32 v57, v130, v131 offset0:140 offset1:206
	v_add_u32_e32 v48, 0x840, v48
	s_cmp_lg_u32 s12, 0x180000
	s_waitcnt lgkmcnt(0)
	s_ashr_i32 s11, s10, 31
	ds_read2_b32 v[8:9], v28 offset1:33
	s_lshl_b64 s[10:11], s[10:11], 1
	s_waitcnt lgkmcnt(0)
	v_cvt_pk_bf16_f32 v8, v8, v9
	ds_read2_b32 v[10:11], v28 offset0:66 offset1:99
	v_add_u32_e32 v12, s26, v27
	s_add_u32 s8, s8, s10
	s_waitcnt lgkmcnt(0)
	v_cvt_pk_bf16_f32 v9, v10, v11
	ds_read2_b32 v[10:11], v28 offset0:132 offset1:165
	v_ashrrev_i32_e32 v13, 31, v12
	s_addc_u32 s9, s9, s11
	s_waitcnt lgkmcnt(0)
	v_cvt_pk_bf16_f32 v10, v10, v11
	ds_read2_b32 v[14:15], v28 offset0:198 offset1:231
	v_lshlrev_b64 v[12:13], 11, v[12:13]
	v_lshl_add_u64 v[16:17], s[8:9], 0, v[0:1]
	s_waitcnt lgkmcnt(0)
	v_cvt_pk_bf16_f32 v11, v14, v15
	ds_read2_b32 v[14:15], v28 offset0:8 offset1:41
	v_lshl_add_u64 v[12:13], v[16:17], 0, v[12:13]
	global_store_dwordx4 v[12:13], v[8:11], off sc0 sc1
	s_waitcnt lgkmcnt(0)
	s_nop 0
	v_cvt_pk_bf16_f32 v8, v14, v15
	v_add_u32_e32 v14, s26, v29
	v_ashrrev_i32_e32 v15, 31, v14
	ds_read2_b32 v[10:11], v28 offset0:74 offset1:107
	v_lshlrev_b64 v[14:15], 11, v[14:15]
	s_waitcnt lgkmcnt(0)
	v_cvt_pk_bf16_f32 v9, v10, v11
	ds_read2_b32 v[10:11], v28 offset0:140 offset1:173
	v_lshl_add_u64 v[14:15], v[16:17], 0, v[14:15]
	s_waitcnt lgkmcnt(0)
	v_cvt_pk_bf16_f32 v10, v10, v11
	ds_read2_b32 v[12:13], v28 offset0:206 offset1:239
	s_waitcnt lgkmcnt(0)
	v_cvt_pk_bf16_f32 v11, v12, v13
	global_store_dwordx4 v[14:15], v[8:11], off sc0 sc1
	v_add_u32_e32 v14, s26, v30
	ds_read2_b32 v[12:13], v28 offset0:16 offset1:49
	s_waitcnt lgkmcnt(0)
	v_cvt_pk_bf16_f32 v8, v12, v13
	ds_read2_b32 v[10:11], v28 offset0:82 offset1:115
	v_ashrrev_i32_e32 v15, 31, v14
	s_waitcnt lgkmcnt(0)
	v_cvt_pk_bf16_f32 v9, v10, v11
	ds_read2_b32 v[10:11], v28 offset0:148 offset1:181
	v_lshlrev_b64 v[14:15], 11, v[14:15]
	s_waitcnt lgkmcnt(0)
	v_cvt_pk_bf16_f32 v10, v10, v11
	ds_read2_b32 v[12:13], v28 offset0:214 offset1:247
	s_waitcnt lgkmcnt(0)
	v_cvt_pk_bf16_f32 v11, v12, v13
	v_lshl_add_u64 v[14:15], v[16:17], 0, v[14:15]
	ds_read2_b32 v[12:13], v28 offset0:24 offset1:57
	global_store_dwordx4 v[14:15], v[8:11], off sc0 sc1
	v_add_u32_e32 v14, s26, v31
	v_ashrrev_i32_e32 v15, 31, v14
	s_waitcnt lgkmcnt(0)
	v_cvt_pk_bf16_f32 v8, v12, v13
	ds_read2_b32 v[10:11], v28 offset0:90 offset1:123
	s_waitcnt lgkmcnt(0)
	v_cvt_pk_bf16_f32 v9, v10, v11
	ds_read2_b32 v[10:11], v28 offset0:156 offset1:189
	s_waitcnt lgkmcnt(0)
	v_cvt_pk_bf16_f32 v10, v10, v11
	ds_read2_b32 v[12:13], v28 offset0:222 offset1:255
	v_lshlrev_b64 v[14:15], 11, v[14:15]
	s_waitcnt lgkmcnt(0)
	v_cvt_pk_bf16_f32 v11, v12, v13
	v_lshl_add_u64 v[12:13], v[16:17], 0, v[14:15]
	global_store_dwordx4 v[12:13], v[8:11], off sc0 sc1
	s_waitcnt lgkmcnt(0)
	s_branch .LBB0_1324

; #define LAS __attribute__((address_space(3)))
; #define LDS_WAIT() asm volatile("s_waitcnt lgkmcnt(0)" ::: "memory")
; template <class T> __device__ __forceinline__ T ntload(const T* p) { return __builtin_nontemporal_load(p); }
; __device__ __forceinline__ void tr_item(const float* W, int ldw, int k0, int n0, bf16_t* WT, int ldt, int drow0, LAS float* scr, int lane) {
; #pragma unroll 8
;     for (int i = 0; i < 32; ++i) { const int kk = 2 * i + (lane >> 5); scr[kk * 33 + (lane & 31)] = ntload(W + (size_t)(k0 + kk) * ldw + n0 + (lane & 31)); }
;     LDS_WAIT();
; __device__ __forceinline__ void convert_layer(int l, LAS unsigned char* lds, int sw) {
;     ...
;             else { const int r = it - 3072, which = r >> 8, r2 = r & 255, h = r2 >> 5, r3 = r2 & 31, kb = r3 >> 3, nb = r3 & 7, n0 = 32 * nb;
;                 const float* W = argp(which ? I_BGXW : I_BGAW) + (size_t)(j * 8 + h) * 256 * 256;
;                 tr_item(W, 256, 64 * kb, n0, Wgate, 256, (2 * h + (n0 >> 7)) * 256 + which * 128 + (n0 & 127), scr, lane); }
.LBB0_1349:
	v_lshl_add_u64 v[50:51], v[26:27], 0, s[6:7]
	v_lshl_add_u64 v[52:53], v[24:25], 0, s[6:7]
	v_lshl_add_u64 v[54:55], v[22:23], 0, s[6:7]
	v_lshl_add_u64 v[56:57], v[20:21], 0, s[6:7]
	v_lshl_add_u64 v[58:59], v[18:19], 0, s[6:7]
	v_lshl_add_u64 v[60:61], v[16:17], 0, s[6:7]
	v_lshl_add_u64 v[62:63], v[14:15], 0, s[6:7]
	v_lshl_add_u64 v[64:65], v[12:13], 0, s[6:7]
	global_load_dword v100, v[50:51], off nt
	global_load_dword v101, v[52:53], off nt
	global_load_dword v102, v[54:55], off nt
	global_load_dword v103, v[56:57], off nt
	global_load_dword v104, v[58:59], off nt
	global_load_dword v105, v[60:61], off nt
	global_load_dword v106, v[62:63], off nt
	global_load_dword v107, v[64:65], off nt
	s_add_u32 s6, s6, 0x4000
	s_addc_u32 s7, s7, 0
	v_lshl_add_u64 v[50:51], v[26:27], 0, s[6:7]
	v_lshl_add_u64 v[52:53], v[24:25], 0, s[6:7]
	v_lshl_add_u64 v[54:55], v[22:23], 0, s[6:7]
	v_lshl_add_u64 v[56:57], v[20:21], 0, s[6:7]
	v_lshl_add_u64 v[58:59], v[18:19], 0, s[6:7]
	v_lshl_add_u64 v[60:61], v[16:17], 0, s[6:7]
	v_lshl_add_u64 v[62:63], v[14:15], 0, s[6:7]
	v_lshl_add_u64 v[64:65], v[12:13], 0, s[6:7]
	global_load_dword v108, v[50:51], off nt
	global_load_dword v109, v[52:53], off nt
	global_load_dword v110, v[54:55], off nt
	global_load_dword v111, v[56:57], off nt
	global_load_dword v112, v[58:59], off nt
	global_load_dword v113, v[60:61], off nt
	global_load_dword v114, v[62:63], off nt
	global_load_dword v115, v[64:65], off nt
	s_add_u32 s6, s6, 0x4000
	s_addc_u32 s7, s7, 0
	v_lshl_add_u64 v[50:51], v[26:27], 0, s[6:7]
	v_lshl_add_u64 v[52:53], v[24:25], 0, s[6:7]
	v_lshl_add_u64 v[54:55], v[22:23], 0, s[6:7]
	v_lshl_add_u64 v[56:57], v[20:21], 0, s[6:7]
	v_lshl_add_u64 v[58:59], v[18:19], 0, s[6:7]
	v_lshl_add_u64 v[60:61], v[16:17], 0, s[6:7]
	v_lshl_add_u64 v[62:63], v[14:15], 0, s[6:7]
	v_lshl_add_u64 v[64:65], v[12:13], 0, s[6:7]
	global_load_dword v116, v[50:51], off nt
	global_load_dword v117, v[52:53], off nt
	global_load_dword v118, v[54:55], off nt
	global_load_dword v119, v[56:57], off nt
	global_load_dword v120, v[58:59], off nt
	global_load_dword v121, v[60:61], off nt
	global_load_dword v122, v[62:63], off nt
	global_load_dword v123, v[64:65], off nt
	s_add_u32 s6, s6, 0x4000
	s_addc_u32 s7, s7, 0
	v_lshl_add_u64 v[50:51], v[26:27], 0, s[6:7]
	v_lshl_add_u64 v[52:53], v[24:25], 0, s[6:7]
	v_lshl_add_u64 v[54:55], v[22:23], 0, s[6:7]
	v_lshl_add_u64 v[56:57], v[20:21], 0, s[6:7]
	v_lshl_add_u64 v[58:59], v[18:19], 0, s[6:7]
	v_lshl_add_u64 v[60:61], v[16:17], 0, s[6:7]
	v_lshl_add_u64 v[62:63], v[14:15], 0, s[6:7]
	v_lshl_add_u64 v[64:65], v[12:13], 0, s[6:7]
	global_load_dword v124, v[50:51], off nt
	global_load_dword v125, v[52:53], off nt
	global_load_dword v126, v[54:55], off nt
	global_load_dword v127, v[56:57], off nt
	global_load_dword v128, v[58:59], off nt
	global_load_dword v129, v[60:61], off nt
	global_load_dword v130, v[62:63], off nt
	global_load_dword v131, v[64:65], off nt
	s_add_u32 s6, s6, 0x4000
	s_addc_u32 s7, s7, 0
	v_add_u32_e32 v58, 0x400, v11
	s_waitcnt vmcnt(30)
	ds_write2_b32 v11, v100, v101 offset1:66
	s_waitcnt vmcnt(28)
	ds_write2_b32 v11, v102, v103 offset0:132 offset1:198
	s_waitcnt vmcnt(26)
	ds_write2_b32 v58, v104, v105 offset0:8 offset1:74
	s_waitcnt vmcnt(24)
	ds_write2_b32 v58, v106, v107 offset0:140 offset1:206
	v_add_u32_e32 v11, 0x840, v11
	v_add_u32_e32 v58, 0x400, v11
	s_waitcnt vmcnt(22)
	ds_write2_b32 v11, v108, v109 offset1:66
	s_waitcnt vmcnt(20)
	ds_write2_b32 v11, v110, v111 offset0:132 offset1:198
	s_waitcnt vmcnt(18)
	ds_write2_b32 v58, v112, v113 offset0:8 offset1:74
	s_waitcnt vmcnt(16)
; #define LAS __attribute__((address_space(3)))
; __device__ __forceinline__ unsigned cvt_pk_bf16(float lo, float hi) { unsigned r; asm volatile("v_cvt_pk_bf16_f32 %0, %1, %2" : "=v"(r) : "v"(lo), "v"(hi)); return r; }
; #define LDS_WAIT() asm volatile("s_waitcnt lgkmcnt(0)" ::: "memory")
; __device__ __forceinline__ void tr_item(const float* W, int ldw, int k0, int n0, bf16_t* WT, int ldt, int drow0, LAS float* scr, int lane) {
;     ...
;     const int c = lane & 7;
; #pragma unroll
;     for (int j = 0; j < 4; ++j) { const int n = (lane >> 3) + 8 * j; const LAS float* s = scr + (8 * c) * 33 + n;
;         u32x4 o; o.x = cvt_pk_bf16(s[0 * 33], s[1 * 33]); o.y = cvt_pk_bf16(s[2 * 33], s[3 * 33]); o.z = cvt_pk_bf16(s[4 * 33], s[5 * 33]); o.w = cvt_pk_bf16(s[6 * 33], s[7 * 33]);
;         *(u32x4*)(WT + (size_t)(drow0 + n) * ldt + k0 + 8 * c) = o; }
;     LDS_WAIT();
; __device__ __forceinline__ void convert_layer(int l, LAS unsigned char* lds, int sw) {
;     ...
;             else { const int r = it - 3072, which = r >> 8, r2 = r & 255, h = r2 >> 5, r3 = r2 & 31, kb = r3 >> 3, nb = r3 & 7, n0 = 32 * nb;
;                 const float* W = argp(which ? I_BGXW : I_BGAW) + (size_t)(j * 8 + h) * 256 * 256;
;                 tr_item(W, 256, 64 * kb, n0, Wgate, 256, (2 * h + (n0 >> 7)) * 256 + which * 128 + (n0 & 127), scr, lane); }
	ds_write2_b32 v58, v114, v115 offset0:140 offset1:206
	v_add_u32_e32 v11, 0x840, v11
	v_add_u32_e32 v58, 0x400, v11
	s_waitcnt vmcnt(14)
	ds_write2_b32 v11, v116, v117 offset1:66
	s_waitcnt vmcnt(12)
	ds_write2_b32 v11, v118, v119 offset0:132 offset1:198
	s_waitcnt vmcnt(10)
	ds_write2_b32 v58, v120, v121 offset0:8 offset1:74
	s_waitcnt vmcnt(8)
	ds_write2_b32 v58, v122, v123 offset0:140 offset1:206
	v_add_u32_e32 v11, 0x840, v11
	v_add_u32_e32 v58, 0x400, v11
	s_waitcnt vmcnt(6)
	ds_write2_b32 v11, v124, v125 offset1:66
	s_waitcnt vmcnt(4)
	ds_write2_b32 v11, v126, v127 offset0:132 offset1:198
	s_waitcnt vmcnt(2)
	ds_write2_b32 v58, v128, v129 offset0:8 offset1:74
	s_waitcnt vmcnt(0)
	ds_write2_b32 v58, v130, v131 offset0:140 offset1:206
	v_add_u32_e32 v11, 0x840, v11
	s_cmp_lg_u32 s6, 0x10000
	s_waitcnt lgkmcnt(0)
	s_lshl_b32 s6, s14, 5
	s_lshl_b32 s7, s14, 4
	ds_read2_b32 v[12:13], v30 offset1:33
	s_lshr_b32 s18, s18, 1
	s_and_b32 s20, s7, 0xe00
	s_and_b32 s6, s6, 0x60
	s_waitcnt lgkmcnt(0)
	v_cvt_pk_bf16_f32 v12, v12, v13
	ds_read2_b32 v[14:15], v30 offset0:66 offset1:99
	s_lshl_b32 s19, s14, 6
	s_and_b32 s18, s18, 0x7fffff80
	s_or_b32 s6, s20, s6
	s_waitcnt lgkmcnt(0)
	v_cvt_pk_bf16_f32 v13, v14, v15
	ds_read2_b32 v[14:15], v30 offset0:132 offset1:165
	s_and_b32 s19, s19, 0x100
	s_add_i32 s6, s6, s18
	s_waitcnt lgkmcnt(0)
	v_cvt_pk_bf16_f32 v14, v14, v15
	ds_read2_b32 v[16:17], v30 offset0:198 offset1:231
	s_add_i32 s6, s6, s19
	s_and_b32 s80, s7, 0x180
	s_waitcnt lgkmcnt(0)
	v_cvt_pk_bf16_f32 v15, v16, v17
	v_or_b32_e32 v16, s6, v29
	v_mov_b32_e32 v17, v1
	v_lshl_add_u64 v[18:19], v[2:3], 0, s[80:81]
	v_lshlrev_b64 v[16:17], 9, v[16:17]
	ds_read2_b32 v[20:21], v30 offset0:8 offset1:41
	v_lshl_add_u64 v[16:17], v[18:19], 0, v[16:17]
	global_store_dwordx4 v[16:17], v[12:15], off sc0 sc1
	s_waitcnt lgkmcnt(0)
	s_nop 0
	v_cvt_pk_bf16_f32 v12, v20, v21
	ds_read2_b32 v[14:15], v30 offset0:74 offset1:107
	v_mov_b32_e32 v21, v1
	v_or_b32_e32 v20, s6, v31
	s_waitcnt lgkmcnt(0)
	v_cvt_pk_bf16_f32 v13, v14, v15
	ds_read2_b32 v[14:15], v30 offset0:140 offset1:173
	v_lshlrev_b64 v[20:21], 9, v[20:21]
	s_waitcnt lgkmcnt(0)
	v_cvt_pk_bf16_f32 v14, v14, v15
	ds_read2_b32 v[16:17], v30 offset0:206 offset1:239
	s_waitcnt lgkmcnt(0)
	v_cvt_pk_bf16_f32 v15, v16, v17
	v_lshl_add_u64 v[20:21], v[18:19], 0, v[20:21]
	ds_read2_b32 v[16:17], v30 offset0:16 offset1:49
	global_store_dwordx4 v[20:21], v[12:15], off sc0 sc1
	v_mov_b32_e32 v21, v1
	v_or_b32_e32 v20, s6, v32
	s_waitcnt lgkmcnt(0)
	v_cvt_pk_bf16_f32 v12, v16, v17
	ds_read2_b32 v[14:15], v30 offset0:82 offset1:115
	s_waitcnt lgkmcnt(0)
	v_cvt_pk_bf16_f32 v13, v14, v15
	ds_read2_b32 v[14:15], v30 offset0:148 offset1:181
	v_lshlrev_b64 v[20:21], 9, v[20:21]
	s_waitcnt lgkmcnt(0)
	v_cvt_pk_bf16_f32 v14, v14, v15
	ds_read2_b32 v[16:17], v30 offset0:214 offset1:247
	s_waitcnt lgkmcnt(0)
	v_cvt_pk_bf16_f32 v15, v16, v17
	v_lshl_add_u64 v[20:21], v[18:19], 0, v[20:21]
	ds_read2_b32 v[16:17], v30 offset0:24 offset1:57
	global_store_dwordx4 v[20:21], v[12:15], off sc0 sc1
	v_mov_b32_e32 v21, v1
	v_or_b32_e32 v20, s6, v33
	s_waitcnt lgkmcnt(0)
	v_cvt_pk_bf16_f32 v12, v16, v17
	ds_read2_b32 v[14:15], v30 offset0:90 offset1:123
	s_waitcnt lgkmcnt(0)
	v_cvt_pk_bf16_f32 v13, v14, v15
	ds_read2_b32 v[14:15], v30 offset0:156 offset1:189
	s_waitcnt lgkmcnt(0)
	v_cvt_pk_bf16_f32 v14, v14, v15
	ds_read2_b32 v[16:17], v30 offset0:222 offset1:255
	v_lshlrev_b64 v[20:21], 9, v[20:21]
	s_waitcnt lgkmcnt(0)
	v_cvt_pk_bf16_f32 v15, v16, v17
	v_lshl_add_u64 v[16:17], v[18:19], 0, v[20:21]
	global_store_dwordx4 v[16:17], v[12:15], off sc0 sc1
	s_waitcnt lgkmcnt(0)
	s_mov_b64 s[6:7], 0

; #define LAS __attribute__((address_space(3)))
; #define LDS_WAIT() asm volatile("s_waitcnt lgkmcnt(0)" ::: "memory")
; template <class T> __device__ __forceinline__ T ntload(const T* p) { return __builtin_nontemporal_load(p); }
; __device__ __forceinline__ void tr_item(const float* W, int ldw, int k0, int n0, bf16_t* WT, int ldt, int drow0, LAS float* scr, int lane) {
; #pragma unroll 8
;     for (int i = 0; i < 32; ++i) { const int kk = 2 * i + (lane >> 5); scr[kk * 33 + (lane & 31)] = ntload(W + (size_t)(k0 + kk) * ldw + n0 + (lane & 31)); }
;     LDS_WAIT();
; __device__ __forceinline__ void convert_layer(int l, LAS unsigned char* lds, int sw) {
;     ...
;             else if (it < 3072) { const int r = it - 2048, kb = r >> 5, nb = r & 31;
;                 tr_item(argp(I_BWOUT) + (size_t)j * 2048 * 1024, 1024, 64 * kb, 32 * nb, Wout, 2048, 32 * nb, scr, lane); }
.LBB0_1353:
	v_lshl_add_u64 v[50:51], v[26:27], 0, s[6:7]
	v_lshl_add_u64 v[52:53], v[24:25], 0, s[6:7]
	v_lshl_add_u64 v[54:55], v[22:23], 0, s[6:7]
	v_lshl_add_u64 v[56:57], v[20:21], 0, s[6:7]
	v_lshl_add_u64 v[58:59], v[18:19], 0, s[6:7]
	v_lshl_add_u64 v[60:61], v[16:17], 0, s[6:7]
	v_lshl_add_u64 v[62:63], v[14:15], 0, s[6:7]
	v_lshl_add_u64 v[64:65], v[12:13], 0, s[6:7]
	global_load_dword v100, v[50:51], off nt
	global_load_dword v101, v[52:53], off nt
	global_load_dword v102, v[54:55], off nt
	global_load_dword v103, v[56:57], off nt
	global_load_dword v104, v[58:59], off nt
	global_load_dword v105, v[60:61], off nt
	global_load_dword v106, v[62:63], off nt
	global_load_dword v107, v[64:65], off nt
	s_add_u32 s6, s6, 0x10000
	s_addc_u32 s7, s7, 0
	v_lshl_add_u64 v[50:51], v[26:27], 0, s[6:7]
	v_lshl_add_u64 v[52:53], v[24:25], 0, s[6:7]
	v_lshl_add_u64 v[54:55], v[22:23], 0, s[6:7]
	v_lshl_add_u64 v[56:57], v[20:21], 0, s[6:7]
	v_lshl_add_u64 v[58:59], v[18:19], 0, s[6:7]
	v_lshl_add_u64 v[60:61], v[16:17], 0, s[6:7]
	v_lshl_add_u64 v[62:63], v[14:15], 0, s[6:7]
	v_lshl_add_u64 v[64:65], v[12:13], 0, s[6:7]
	global_load_dword v108, v[50:51], off nt
	global_load_dword v109, v[52:53], off nt
	global_load_dword v110, v[54:55], off nt
	global_load_dword v111, v[56:57], off nt
	global_load_dword v112, v[58:59], off nt
	global_load_dword v113, v[60:61], off nt
	global_load_dword v114, v[62:63], off nt
	global_load_dword v115, v[64:65], off nt
	s_add_u32 s6, s6, 0x10000
	s_addc_u32 s7, s7, 0
	v_lshl_add_u64 v[50:51], v[26:27], 0, s[6:7]
	v_lshl_add_u64 v[52:53], v[24:25], 0, s[6:7]
	v_lshl_add_u64 v[54:55], v[22:23], 0, s[6:7]
	v_lshl_add_u64 v[56:57], v[20:21], 0, s[6:7]
	v_lshl_add_u64 v[58:59], v[18:19], 0, s[6:7]
	v_lshl_add_u64 v[60:61], v[16:17], 0, s[6:7]
	v_lshl_add_u64 v[62:63], v[14:15], 0, s[6:7]
	v_lshl_add_u64 v[64:65], v[12:13], 0, s[6:7]
	global_load_dword v116, v[50:51], off nt
	global_load_dword v117, v[52:53], off nt
	global_load_dword v118, v[54:55], off nt
	global_load_dword v119, v[56:57], off nt
	global_load_dword v120, v[58:59], off nt
	global_load_dword v121, v[60:61], off nt
	global_load_dword v122, v[62:63], off nt
	global_load_dword v123, v[64:65], off nt
	s_add_u32 s6, s6, 0x10000
	s_addc_u32 s7, s7, 0
	v_lshl_add_u64 v[50:51], v[26:27], 0, s[6:7]
	v_lshl_add_u64 v[52:53], v[24:25], 0, s[6:7]
	v_lshl_add_u64 v[54:55], v[22:23], 0, s[6:7]
	v_lshl_add_u64 v[56:57], v[20:21], 0, s[6:7]
	v_lshl_add_u64 v[58:59], v[18:19], 0, s[6:7]
	v_lshl_add_u64 v[60:61], v[16:17], 0, s[6:7]
	v_lshl_add_u64 v[62:63], v[14:15], 0, s[6:7]
	v_lshl_add_u64 v[64:65], v[12:13], 0, s[6:7]
	global_load_dword v124, v[50:51], off nt
	global_load_dword v125, v[52:53], off nt
	global_load_dword v126, v[54:55], off nt
	global_load_dword v127, v[56:57], off nt
	global_load_dword v128, v[58:59], off nt
	global_load_dword v129, v[60:61], off nt
	global_load_dword v130, v[62:63], off nt
	global_load_dword v131, v[64:65], off nt
	s_add_u32 s6, s6, 0x10000
	s_addc_u32 s7, s7, 0
	v_add_u32_e32 v58, 0x400, v11
	s_waitcnt vmcnt(30)
	ds_write2_b32 v11, v100, v101 offset1:66
	s_waitcnt vmcnt(28)
	ds_write2_b32 v11, v102, v103 offset0:132 offset1:198
	s_waitcnt vmcnt(26)
	ds_write2_b32 v58, v104, v105 offset0:8 offset1:74
	s_waitcnt vmcnt(24)
	ds_write2_b32 v58, v106, v107 offset0:140 offset1:206
	v_add_u32_e32 v11, 0x840, v11
	v_add_u32_e32 v58, 0x400, v11
	s_waitcnt vmcnt(22)
	ds_write2_b32 v11, v108, v109 offset1:66
	s_waitcnt vmcnt(20)
	ds_write2_b32 v11, v110, v111 offset0:132 offset1:198
	s_waitcnt vmcnt(18)
; #define LAS __attribute__((address_space(3)))
; __device__ __forceinline__ unsigned cvt_pk_bf16(float lo, float hi) { unsigned r; asm volatile("v_cvt_pk_bf16_f32 %0, %1, %2" : "=v"(r) : "v"(lo), "v"(hi)); return r; }
; #define LDS_WAIT() asm volatile("s_waitcnt lgkmcnt(0)" ::: "memory")
; __device__ __forceinline__ void tr_item(const float* W, int ldw, int k0, int n0, bf16_t* WT, int ldt, int drow0, LAS float* scr, int lane) {
;     ...
;     const int c = lane & 7;
; #pragma unroll
;     for (int j = 0; j < 4; ++j) { const int n = (lane >> 3) + 8 * j; const LAS float* s = scr + (8 * c) * 33 + n;
;         u32x4 o; o.x = cvt_pk_bf16(s[0 * 33], s[1 * 33]); o.y = cvt_pk_bf16(s[2 * 33], s[3 * 33]); o.z = cvt_pk_bf16(s[4 * 33], s[5 * 33]); o.w = cvt_pk_bf16(s[6 * 33], s[7 * 33]);
;         *(u32x4*)(WT + (size_t)(drow0 + n) * ldt + k0 + 8 * c) = o; }
;     LDS_WAIT();
	ds_write2_b32 v58, v112, v113 offset0:8 offset1:74
	s_waitcnt vmcnt(16)
	ds_write2_b32 v58, v114, v115 offset0:140 offset1:206
	v_add_u32_e32 v11, 0x840, v11
	v_add_u32_e32 v58, 0x400, v11
	s_waitcnt vmcnt(14)
	ds_write2_b32 v11, v116, v117 offset1:66
	s_waitcnt vmcnt(12)
	ds_write2_b32 v11, v118, v119 offset0:132 offset1:198
	s_waitcnt vmcnt(10)
	ds_write2_b32 v58, v120, v121 offset0:8 offset1:74
	s_waitcnt vmcnt(8)
	ds_write2_b32 v58, v122, v123 offset0:140 offset1:206
	v_add_u32_e32 v11, 0x840, v11
	v_add_u32_e32 v58, 0x400, v11
	s_waitcnt vmcnt(6)
	ds_write2_b32 v11, v124, v125 offset1:66
	s_waitcnt vmcnt(4)
	ds_write2_b32 v11, v126, v127 offset0:132 offset1:198
	s_waitcnt vmcnt(2)
	ds_write2_b32 v58, v128, v129 offset0:8 offset1:74
	s_waitcnt vmcnt(0)
	ds_write2_b32 v58, v130, v131 offset0:140 offset1:206
	v_add_u32_e32 v11, 0x840, v11
	s_cmp_lg_u32 s6, 0x40000
	s_waitcnt lgkmcnt(0)
	s_lshl_b32 s6, s14, 1
	s_lshl_b32 s7, s14, 5
	ds_read2_b32 v[12:13], v30 offset1:33
	s_and_b32 s17, s6, 0x1fc0
	s_and_b32 s6, s7, 0x3e0
	s_waitcnt lgkmcnt(0)
	v_cvt_pk_bf16_f32 v12, v12, v13
	ds_read2_b32 v[14:15], v30 offset0:66 offset1:99
	s_add_i32 s80, s17, 0xfffff000
	v_or_b32_e32 v11, s6, v29
	s_waitcnt lgkmcnt(0)
	v_cvt_pk_bf16_f32 v13, v14, v15
	ds_read2_b32 v[14:15], v30 offset0:132 offset1:165
	v_mov_b32_e32 v17, v1
	v_lshl_add_u64 v[20:21], s[80:81], 1, v[4:5]
	v_lshlrev_b32_e32 v16, 12, v11
	s_waitcnt lgkmcnt(0)
	v_cvt_pk_bf16_f32 v14, v14, v15
	ds_read2_b32 v[18:19], v30 offset0:198 offset1:231
	s_waitcnt lgkmcnt(0)
	v_cvt_pk_bf16_f32 v15, v18, v19
	v_lshl_add_u64 v[16:17], v[20:21], 0, v[16:17]
	ds_read2_b32 v[18:19], v30 offset0:8 offset1:41
	global_store_dwordx4 v[16:17], v[12:15], off sc0 sc1
	v_or_b32_e32 v11, s6, v31
	s_waitcnt lgkmcnt(0)
	v_cvt_pk_bf16_f32 v12, v18, v19
	ds_read2_b32 v[14:15], v30 offset0:74 offset1:107
	s_waitcnt lgkmcnt(0)
	v_cvt_pk_bf16_f32 v13, v14, v15
	ds_read2_b32 v[14:15], v30 offset0:140 offset1:173
	v_mov_b32_e32 v19, v1
	v_lshlrev_b32_e32 v18, 12, v11
	s_waitcnt lgkmcnt(0)
	v_cvt_pk_bf16_f32 v14, v14, v15
	ds_read2_b32 v[16:17], v30 offset0:206 offset1:239
	s_waitcnt lgkmcnt(0)
	v_cvt_pk_bf16_f32 v15, v16, v17
	v_lshl_add_u64 v[18:19], v[20:21], 0, v[18:19]
	ds_read2_b32 v[16:17], v30 offset0:16 offset1:49
	global_store_dwordx4 v[18:19], v[12:15], off sc0 sc1
	v_or_b32_e32 v11, s6, v32
	v_mov_b32_e32 v19, v1
	s_waitcnt lgkmcnt(0)
	v_cvt_pk_bf16_f32 v12, v16, v17
	ds_read2_b32 v[14:15], v30 offset0:82 offset1:115
	s_waitcnt lgkmcnt(0)
	v_cvt_pk_bf16_f32 v13, v14, v15
	ds_read2_b32 v[14:15], v30 offset0:148 offset1:181
	v_lshlrev_b32_e32 v18, 12, v11
	s_waitcnt lgkmcnt(0)
	v_cvt_pk_bf16_f32 v14, v14, v15
	ds_read2_b32 v[16:17], v30 offset0:214 offset1:247
	s_waitcnt lgkmcnt(0)
	v_cvt_pk_bf16_f32 v15, v16, v17
	v_lshl_add_u64 v[18:19], v[20:21], 0, v[18:19]
	ds_read2_b32 v[16:17], v30 offset0:24 offset1:57
	global_store_dwordx4 v[18:19], v[12:15], off sc0 sc1
	v_or_b32_e32 v11, s6, v33
	v_mov_b32_e32 v19, v1
	s_waitcnt lgkmcnt(0)
	v_cvt_pk_bf16_f32 v12, v16, v17
	ds_read2_b32 v[14:15], v30 offset0:90 offset1:123
	s_waitcnt lgkmcnt(0)
	v_cvt_pk_bf16_f32 v13, v14, v15
	ds_read2_b32 v[14:15], v30 offset0:156 offset1:189
	s_waitcnt lgkmcnt(0)
	v_cvt_pk_bf16_f32 v14, v14, v15
	ds_read2_b32 v[16:17], v30 offset0:222 offset1:255
	v_lshlrev_b32_e32 v18, 12, v11
	s_waitcnt lgkmcnt(0)
	v_cvt_pk_bf16_f32 v15, v16, v17
	v_lshl_add_u64 v[16:17], v[20:21], 0, v[18:19]
	global_store_dwordx4 v[16:17], v[12:15], off sc0 sc1
	s_waitcnt lgkmcnt(0)

; #define LAS __attribute__((address_space(3)))
; #define LDS_WAIT() asm volatile("s_waitcnt lgkmcnt(0)" ::: "memory")
; template <class T> __device__ __forceinline__ T ntload(const T* p) { return __builtin_nontemporal_load(p); }
; __device__ __forceinline__ void tr_item(const float* W, int ldw, int k0, int n0, bf16_t* WT, int ldt, int drow0, LAS float* scr, int lane) {
; #pragma unroll 8
;     for (int i = 0; i < 32; ++i) { const int kk = 2 * i + (lane >> 5); scr[kk * 33 + (lane & 31)] = ntload(W + (size_t)(k0 + kk) * ldw + n0 + (lane & 31)); }
;     LDS_WAIT();
; __device__ __forceinline__ void convert_layer(int l, LAS unsigned char* lds, int sw) {
;     ...
;             if (it < 2048) { const int kb = it >> 7, nb = it & 127, n0 = 32 * nb;
;                 tr_item(argp(I_BWIN) + (size_t)j * 1024 * 4096, 4096, 64 * kb, n0, n0 < 2048 ? Wx : Wg, 1024, n0 & 2047, scr, lane); }
.LBB0_1358:
	v_add_u32_e32 v16, s18, v11
	v_add_u32_e32 v18, 2, v16
	v_add_u32_e32 v20, 4, v16
	v_add_u32_e32 v22, 6, v16
	v_ashrrev_i32_e32 v17, 31, v16
	v_add_u32_e32 v24, 8, v16
	v_add_u32_e32 v26, 10, v16
	v_add_u32_e32 v50, 12, v16
	v_add_u32_e32 v52, 14, v16
	v_ashrrev_i32_e32 v19, 31, v18
	v_ashrrev_i32_e32 v21, 31, v20
	v_ashrrev_i32_e32 v23, 31, v22
	v_lshlrev_b64 v[16:17], 14, v[16:17]
	v_ashrrev_i32_e32 v25, 31, v24
	v_ashrrev_i32_e32 v27, 31, v26
	v_ashrrev_i32_e32 v51, 31, v50
	v_ashrrev_i32_e32 v53, 31, v52
	v_lshlrev_b64 v[18:19], 14, v[18:19]
	v_lshlrev_b64 v[20:21], 14, v[20:21]
	v_lshlrev_b64 v[22:23], 14, v[22:23]
	v_lshl_add_u64 v[16:17], v[12:13], 0, v[16:17]
	v_lshlrev_b64 v[24:25], 14, v[24:25]
	v_lshlrev_b64 v[26:27], 14, v[26:27]
	v_lshlrev_b64 v[50:51], 14, v[50:51]
	v_lshlrev_b64 v[52:53], 14, v[52:53]
	v_lshl_add_u64 v[18:19], v[12:13], 0, v[18:19]
	v_lshl_add_u64 v[20:21], v[12:13], 0, v[20:21]
	v_lshl_add_u64 v[22:23], v[12:13], 0, v[22:23]
	v_lshl_add_u64 v[24:25], v[12:13], 0, v[24:25]
	v_lshl_add_u64 v[26:27], v[12:13], 0, v[26:27]
	v_lshl_add_u64 v[50:51], v[12:13], 0, v[50:51]
	v_lshl_add_u64 v[52:53], v[12:13], 0, v[52:53]
	global_load_dword v100, v[16:17], off nt
	global_load_dword v101, v[18:19], off nt
	global_load_dword v102, v[20:21], off nt
	global_load_dword v103, v[22:23], off nt
	global_load_dword v104, v[24:25], off nt
	global_load_dword v105, v[26:27], off nt
	global_load_dword v106, v[50:51], off nt
	global_load_dword v107, v[52:53], off nt
	s_add_i32 s18, s18, 16
	v_add_u32_e32 v16, s18, v11
	v_add_u32_e32 v18, 2, v16
	v_add_u32_e32 v20, 4, v16
	v_add_u32_e32 v22, 6, v16
	v_ashrrev_i32_e32 v17, 31, v16
	v_add_u32_e32 v24, 8, v16
	v_add_u32_e32 v26, 10, v16
	v_add_u32_e32 v50, 12, v16
	v_add_u32_e32 v52, 14, v16
	v_ashrrev_i32_e32 v19, 31, v18
	v_ashrrev_i32_e32 v21, 31, v20
	v_ashrrev_i32_e32 v23, 31, v22
	v_lshlrev_b64 v[16:17], 14, v[16:17]
	v_ashrrev_i32_e32 v25, 31, v24
	v_ashrrev_i32_e32 v27, 31, v26
	v_ashrrev_i32_e32 v51, 31, v50
	v_ashrrev_i32_e32 v53, 31, v52
	v_lshlrev_b64 v[18:19], 14, v[18:19]
	v_lshlrev_b64 v[20:21], 14, v[20:21]
	v_lshlrev_b64 v[22:23], 14, v[22:23]
	v_lshl_add_u64 v[16:17], v[12:13], 0, v[16:17]
	v_lshlrev_b64 v[24:25], 14, v[24:25]
	v_lshlrev_b64 v[26:27], 14, v[26:27]
	v_lshlrev_b64 v[50:51], 14, v[50:51]
	v_lshlrev_b64 v[52:53], 14, v[52:53]
	v_lshl_add_u64 v[18:19], v[12:13], 0, v[18:19]
	v_lshl_add_u64 v[20:21], v[12:13], 0, v[20:21]
	v_lshl_add_u64 v[22:23], v[12:13], 0, v[22:23]
	v_lshl_add_u64 v[24:25], v[12:13], 0, v[24:25]
	v_lshl_add_u64 v[26:27], v[12:13], 0, v[26:27]
	v_lshl_add_u64 v[50:51], v[12:13], 0, v[50:51]
	v_lshl_add_u64 v[52:53], v[12:13], 0, v[52:53]
	global_load_dword v108, v[16:17], off nt
	global_load_dword v109, v[18:19], off nt
	global_load_dword v110, v[20:21], off nt
	global_load_dword v111, v[22:23], off nt
	global_load_dword v112, v[24:25], off nt
	global_load_dword v113, v[26:27], off nt
	global_load_dword v114, v[50:51], off nt
	global_load_dword v115, v[52:53], off nt
	s_add_i32 s18, s18, 16
	v_add_u32_e32 v16, s18, v11
	v_add_u32_e32 v18, 2, v16
	v_add_u32_e32 v20, 4, v16
	v_add_u32_e32 v22, 6, v16
	v_ashrrev_i32_e32 v17, 31, v16
	v_add_u32_e32 v24, 8, v16
	v_add_u32_e32 v26, 10, v16
	v_add_u32_e32 v50, 12, v16
	v_add_u32_e32 v52, 14, v16
	v_ashrrev_i32_e32 v19, 31, v18
	v_ashrrev_i32_e32 v21, 31, v20
	v_ashrrev_i32_e32 v23, 31, v22
	v_lshlrev_b64 v[16:17], 14, v[16:17]
	v_ashrrev_i32_e32 v25, 31, v24
	v_ashrrev_i32_e32 v27, 31, v26
	v_ashrrev_i32_e32 v51, 31, v50
	v_ashrrev_i32_e32 v53, 31, v52
	v_lshlrev_b64 v[18:19], 14, v[18:19]
	v_lshlrev_b64 v[20:21], 14, v[20:21]
	v_lshlrev_b64 v[22:23], 14, v[22:23]
	v_lshl_add_u64 v[16:17], v[12:13], 0, v[16:17]
	v_lshlrev_b64 v[24:25], 14, v[24:25]
	v_lshlrev_b64 v[26:27], 14, v[26:27]
	v_lshlrev_b64 v[50:51], 14, v[50:51]
	v_lshlrev_b64 v[52:53], 14, v[52:53]
	v_lshl_add_u64 v[18:19], v[12:13], 0, v[18:19]
	v_lshl_add_u64 v[20:21], v[12:13], 0, v[20:21]
	v_lshl_add_u64 v[22:23], v[12:13], 0, v[22:23]
	v_lshl_add_u64 v[24:25], v[12:13], 0, v[24:25]
	v_lshl_add_u64 v[26:27], v[12:13], 0, v[26:27]
	v_lshl_add_u64 v[50:51], v[12:13], 0, v[50:51]
	v_lshl_add_u64 v[52:53], v[12:13], 0, v[52:53]
	global_load_dword v116, v[16:17], off nt
	global_load_dword v117, v[18:19], off nt
	global_load_dword v118, v[20:21], off nt
	global_load_dword v119, v[22:23], off nt
	global_load_dword v120, v[24:25], off nt
	global_load_dword v121, v[26:27], off nt
	global_load_dword v122, v[50:51], off nt
	global_load_dword v123, v[52:53], off nt
	s_add_i32 s18, s18, 16
	v_add_u32_e32 v16, s18, v11
	v_add_u32_e32 v18, 2, v16
	v_add_u32_e32 v20, 4, v16
	v_add_u32_e32 v22, 6, v16
	v_ashrrev_i32_e32 v17, 31, v16
	v_add_u32_e32 v24, 8, v16
	v_add_u32_e32 v26, 10, v16
	v_add_u32_e32 v50, 12, v16
	v_add_u32_e32 v52, 14, v16
	v_ashrrev_i32_e32 v19, 31, v18
	v_ashrrev_i32_e32 v21, 31, v20
	v_ashrrev_i32_e32 v23, 31, v22
	v_lshlrev_b64 v[16:17], 14, v[16:17]
	v_ashrrev_i32_e32 v25, 31, v24
	v_ashrrev_i32_e32 v27, 31, v26
	v_ashrrev_i32_e32 v51, 31, v50
	v_ashrrev_i32_e32 v53, 31, v52
	v_lshlrev_b64 v[18:19], 14, v[18:19]
	v_lshlrev_b64 v[20:21], 14, v[20:21]
	v_lshlrev_b64 v[22:23], 14, v[22:23]
	v_lshl_add_u64 v[16:17], v[12:13], 0, v[16:17]
	v_lshlrev_b64 v[24:25], 14, v[24:25]
	v_lshlrev_b64 v[26:27], 14, v[26:27]
	v_lshlrev_b64 v[50:51], 14, v[50:51]
	v_lshlrev_b64 v[52:53], 14, v[52:53]
	v_lshl_add_u64 v[18:19], v[12:13], 0, v[18:19]
	v_lshl_add_u64 v[20:21], v[12:13], 0, v[20:21]
	v_lshl_add_u64 v[22:23], v[12:13], 0, v[22:23]
	v_lshl_add_u64 v[24:25], v[12:13], 0, v[24:25]
	v_lshl_add_u64 v[26:27], v[12:13], 0, v[26:27]
	v_lshl_add_u64 v[50:51], v[12:13], 0, v[50:51]
	v_lshl_add_u64 v[52:53], v[12:13], 0, v[52:53]
	global_load_dword v124, v[16:17], off nt
	global_load_dword v125, v[18:19], off nt
	global_load_dword v126, v[20:21], off nt
	global_load_dword v127, v[22:23], off nt
	global_load_dword v128, v[24:25], off nt
	global_load_dword v129, v[26:27], off nt
	global_load_dword v130, v[50:51], off nt
	global_load_dword v131, v[52:53], off nt
	s_add_i32 s18, s18, 16
	v_add_u32_e32 v23, 0x400, v14
	s_waitcnt vmcnt(30)
; #define LAS __attribute__((address_space(3)))
; __device__ __forceinline__ unsigned cvt_pk_bf16(float lo, float hi) { unsigned r; asm volatile("v_cvt_pk_bf16_f32 %0, %1, %2" : "=v"(r) : "v"(lo), "v"(hi)); return r; }
; #define LDS_WAIT() asm volatile("s_waitcnt lgkmcnt(0)" ::: "memory")
; __device__ __forceinline__ void tr_item(const float* W, int ldw, int k0, int n0, bf16_t* WT, int ldt, int drow0, LAS float* scr, int lane) {
;     ...
;     const int c = lane & 7;
; #pragma unroll
;     for (int j = 0; j < 4; ++j) { const int n = (lane >> 3) + 8 * j; const LAS float* s = scr + (8 * c) * 33 + n;
;         u32x4 o; o.x = cvt_pk_bf16(s[0 * 33], s[1 * 33]); o.y = cvt_pk_bf16(s[2 * 33], s[3 * 33]); o.z = cvt_pk_bf16(s[4 * 33], s[5 * 33]); o.w = cvt_pk_bf16(s[6 * 33], s[7 * 33]);
;         *(u32x4*)(WT + (size_t)(drow0 + n) * ldt + k0 + 8 * c) = o; }
;     LDS_WAIT();
; __device__ __forceinline__ void convert_layer(int l, LAS unsigned char* lds, int sw) {
;     ...
;         for (int it = gw; it < 3584; it += NGW) {
;             if (it < 2048) { const int kb = it >> 7, nb = it & 127, n0 = 32 * nb;
;                 tr_item(argp(I_BWIN) + (size_t)j * 1024 * 4096, 4096, 64 * kb, n0, n0 < 2048 ? Wx : Wg, 1024, n0 & 2047, scr, lane); }
	ds_write2_b32 v14, v100, v101 offset1:66
	s_waitcnt vmcnt(28)
	ds_write2_b32 v14, v102, v103 offset0:132 offset1:198
	s_waitcnt vmcnt(26)
	ds_write2_b32 v23, v104, v105 offset0:8 offset1:74
	s_waitcnt vmcnt(24)
	ds_write2_b32 v23, v106, v107 offset0:140 offset1:206
	v_add_u32_e32 v14, 0x840, v14
	v_add_u32_e32 v23, 0x400, v14
	s_waitcnt vmcnt(22)
	ds_write2_b32 v14, v108, v109 offset1:66
	s_waitcnt vmcnt(20)
	ds_write2_b32 v14, v110, v111 offset0:132 offset1:198
	s_waitcnt vmcnt(18)
	ds_write2_b32 v23, v112, v113 offset0:8 offset1:74
	s_waitcnt vmcnt(16)
	ds_write2_b32 v23, v114, v115 offset0:140 offset1:206
	v_add_u32_e32 v14, 0x840, v14
	v_add_u32_e32 v23, 0x400, v14
	s_waitcnt vmcnt(14)
	ds_write2_b32 v14, v116, v117 offset1:66
	s_waitcnt vmcnt(12)
	ds_write2_b32 v14, v118, v119 offset0:132 offset1:198
	s_waitcnt vmcnt(10)
	ds_write2_b32 v23, v120, v121 offset0:8 offset1:74
	s_waitcnt vmcnt(8)
	ds_write2_b32 v23, v122, v123 offset0:140 offset1:206
	v_add_u32_e32 v14, 0x840, v14
	v_add_u32_e32 v23, 0x400, v14
	s_waitcnt vmcnt(6)
	ds_write2_b32 v14, v124, v125 offset1:66
	s_waitcnt vmcnt(4)
	ds_write2_b32 v14, v126, v127 offset0:132 offset1:198
	s_waitcnt vmcnt(2)
	ds_write2_b32 v23, v128, v129 offset0:8 offset1:74
	s_waitcnt vmcnt(0)
	ds_write2_b32 v23, v130, v131 offset0:140 offset1:206
	v_add_u32_e32 v14, 0x840, v14
	s_cmp_lg_u32 s18, 64
	s_cmpk_lt_u32 s17, 0x800
	s_cselect_b32 s17, 0, 0x400000
	s_waitcnt lgkmcnt(0)
	s_add_u32 s18, s0, s17
	ds_read2_b32 v[12:13], v30 offset1:33
	s_addc_u32 s19, s1, 0
	s_and_b32 s17, s7, 0x7e0
	s_ashr_i32 s7, s6, 31
	s_waitcnt lgkmcnt(0)
	v_cvt_pk_bf16_f32 v12, v12, v13
	ds_read2_b32 v[14:15], v30 offset0:66 offset1:99
	s_lshl_b64 s[6:7], s[6:7], 1
	s_waitcnt lgkmcnt(0)
	v_cvt_pk_bf16_f32 v13, v14, v15
	ds_read2_b32 v[14:15], v30 offset0:132 offset1:165
	s_add_u32 s6, s18, s6
	v_mov_b32_e32 v11, v1
	s_waitcnt lgkmcnt(0)
	v_cvt_pk_bf16_f32 v14, v14, v15
	v_or_b32_e32 v15, s17, v29
	s_addc_u32 s7, s19, s7
	v_mov_b32_e32 v17, v1
	v_lshlrev_b32_e32 v16, 11, v15
	v_lshl_add_u64 v[20:21], s[6:7], 0, v[10:11]
	ds_read2_b32 v[18:19], v30 offset0:198 offset1:231
	s_waitcnt lgkmcnt(0)
	v_cvt_pk_bf16_f32 v15, v18, v19
	v_lshl_add_u64 v[16:17], v[20:21], 0, v[16:17]
	ds_read2_b32 v[18:19], v30 offset0:8 offset1:41
	global_store_dwordx4 v[16:17], v[12:15], off sc0 sc1
	v_or_b32_e32 v11, s17, v31
	s_waitcnt lgkmcnt(0)
	v_cvt_pk_bf16_f32 v12, v18, v19
	ds_read2_b32 v[14:15], v30 offset0:74 offset1:107
	s_waitcnt lgkmcnt(0)
	v_cvt_pk_bf16_f32 v13, v14, v15
	ds_read2_b32 v[14:15], v30 offset0:140 offset1:173
	v_mov_b32_e32 v19, v1
	v_lshlrev_b32_e32 v18, 11, v11
	s_waitcnt lgkmcnt(0)
	v_cvt_pk_bf16_f32 v14, v14, v15
	ds_read2_b32 v[16:17], v30 offset0:206 offset1:239
	s_waitcnt lgkmcnt(0)
	v_cvt_pk_bf16_f32 v15, v16, v17
	v_lshl_add_u64 v[18:19], v[20:21], 0, v[18:19]
	ds_read2_b32 v[16:17], v30 offset0:16 offset1:49
	global_store_dwordx4 v[18:19], v[12:15], off sc0 sc1
	v_or_b32_e32 v11, s17, v32
	v_mov_b32_e32 v19, v1
	s_waitcnt lgkmcnt(0)
	v_cvt_pk_bf16_f32 v12, v16, v17
	ds_read2_b32 v[14:15], v30 offset0:82 offset1:115
	s_waitcnt lgkmcnt(0)
	v_cvt_pk_bf16_f32 v13, v14, v15
	ds_read2_b32 v[14:15], v30 offset0:148 offset1:181
	v_lshlrev_b32_e32 v18, 11, v11
	s_waitcnt lgkmcnt(0)
	v_cvt_pk_bf16_f32 v14, v14, v15
	ds_read2_b32 v[16:17], v30 offset0:214 offset1:247
	s_waitcnt lgkmcnt(0)
	v_cvt_pk_bf16_f32 v15, v16, v17
	v_lshl_add_u64 v[18:19], v[20:21], 0, v[18:19]
	ds_read2_b32 v[16:17], v30 offset0:24 offset1:57
	global_store_dwordx4 v[18:19], v[12:15], off sc0 sc1
	v_or_b32_e32 v11, s17, v33
	v_mov_b32_e32 v19, v1
	s_waitcnt lgkmcnt(0)
	v_cvt_pk_bf16_f32 v12, v16, v17
	ds_read2_b32 v[14:15], v30 offset0:90 offset1:123
	s_waitcnt lgkmcnt(0)
	v_cvt_pk_bf16_f32 v13, v14, v15
	ds_read2_b32 v[14:15], v30 offset0:156 offset1:189
	s_waitcnt lgkmcnt(0)
	v_cvt_pk_bf16_f32 v14, v14, v15
	ds_read2_b32 v[16:17], v30 offset0:222 offset1:255
	v_lshlrev_b32_e32 v18, 11, v11
	s_waitcnt lgkmcnt(0)
	v_cvt_pk_bf16_f32 v15, v16, v17
	v_lshl_add_u64 v[16:17], v[20:21], 0, v[18:19]
	global_store_dwordx4 v[16:17], v[12:15], off sc0 sc1
	s_waitcnt lgkmcnt(0)
	s_branch .LBB0_1345

; __device__ __forceinline__ unsigned xb_add(unsigned* p, unsigned v) { return __hip_atomic_fetch_add(p, v, __ATOMIC_RELAXED, __HIP_MEMORY_SCOPE_AGENT); }
; __device__ __forceinline__ void xcd_barrier(const XcdBarrier& b, int local) {
;     ...
;             __builtin_amdgcn_fence(__ATOMIC_RELEASE, "agent");
;             asm volatile("s_waitcnt vmcnt(0)" ::: "memory");
;             const unsigned og = xb_add(&bar[XB_TOP], 1u);
;             const unsigned tg = og / nx;
;             if (og + 1u == (tg + 1u) * nx) xb_add(&bar[XB_TOPGEN], 1u);
.LBB0_1393:
	s_mov_b64 s[6:7], exec
	s_waitcnt lgkmcnt(0)
	s_waitcnt vmcnt(0)
	v_mbcnt_lo_u32_b32 v2, s6, 0
	v_mbcnt_hi_u32_b32 v2, s7, v2
	v_cmp_eq_u32_e32 vcc, 0, v2
	s_and_saveexec_b64 s[8:9], vcc
	s_cbranch_execz .LBB0_1395
	s_bcnt1_i32_b64 s6, s[6:7]
	v_mov_b32_e32 v3, s6
	v_mov_b32_e32 v4, 0x3000
	global_atomic_add v3, v4, v3, s[4:5] offset:1024 sc0
